# GVTF stores sc1 too
# speedup vs baseline: 1.0035x; 1.0035x over previous
.LBB0_186:
	s_mov_b32 s4, 0x3856241d
	v_and_b32_e32 v163, 0x7fffffff, v125
	v_and_b32_e32 v162, 0x7fffffff, v124
	v_mov_b64_e32 v[152:153], s[4:5]
	v_pk_fma_f32 v[164:165], v[162:163], s[94:95], v[152:153] op_sel_hi:[1,0,0]
	v_max_f32_e32 v124, v124, v124
	v_pk_fma_f32 v[164:165], v[162:163], v[164:165], s[96:97] op_sel_hi:[1,1,0]
	v_max_f32_e32 v125, v125, v125
	v_pk_fma_f32 v[164:165], v[162:163], v[164:165], s[98:99] op_sel_hi:[1,1,0]
	v_and_b32_e32 v155, 0x7fffffff, v127
	v_pk_fma_f32 v[164:165], v[162:163], v[164:165], s[40:41] op_sel_hi:[1,1,0]
	v_and_b32_e32 v154, 0x7fffffff, v126
	v_pk_fma_f32 v[164:165], v[162:163], v[164:165], s[74:75] op_sel_hi:[1,1,0]
	v_max_f32_e32 v124, 0, v124
	v_pk_fma_f32 v[164:165], v[162:163], v[164:165], s[76:77] op_sel_hi:[1,1,0]
	v_max_f32_e32 v125, 0, v125
	v_pk_mul_f32 v[164:165], v[164:165], v[164:165]
	v_max_f32_e32 v126, v126, v126
	v_pk_mul_f32 v[164:165], v[164:165], v[164:165]
	v_max_f32_e32 v127, v127, v127
	v_pk_mul_f32 v[164:165], v[164:165], v[164:165]
	v_max_f32_e32 v126, 0, v126
	v_pk_mul_f32 v[164:165], v[164:165], v[164:165]
	v_max_f32_e32 v127, 0, v127
	v_rcp_f32_e32 v164, v164
	v_rcp_f32_e32 v165, v165
	s_lshl_b32 s0, s11, 1
	s_lshl_b32 s82, s86, 1
	s_ashr_i32 s1, s0, 31
	v_pk_fma_f32 v[124:125], v[162:163], v[164:165], v[124:125] neg_lo:[1,0,0] neg_hi:[1,0,0]
	v_pk_fma_f32 v[162:163], v[154:155], s[94:95], v[152:153] op_sel_hi:[1,0,0]
	s_ashr_i32 s83, s82, 31
	v_pk_fma_f32 v[162:163], v[154:155], v[162:163], s[96:97] op_sel_hi:[1,1,0]
	s_lshl_b64 vcc, s[82:83], 8
	v_pk_fma_f32 v[162:163], v[154:155], v[162:163], s[98:99] op_sel_hi:[1,1,0]
	s_lshl_b64 s[4:5], s[0:1], 5
	v_pk_fma_f32 v[162:163], v[154:155], v[162:163], s[40:41] op_sel_hi:[1,1,0]
	s_add_u32 s1, s4, s41
	v_pk_fma_f32 v[162:163], v[154:155], v[162:163], s[74:75] op_sel_hi:[1,1,0]
	s_addc_u32 s11, s5, 0
	v_pk_fma_f32 v[162:163], v[154:155], v[162:163], s[76:77] op_sel_hi:[1,1,0]
	s_add_u32 s12, vcc_lo, s1
	v_pk_mul_f32 v[162:163], v[162:163], v[162:163]
	s_addc_u32 s13, vcc_hi, s11
	v_pk_mul_f32 v[162:163], v[162:163], v[162:163]
	s_nop 0
	v_pk_mul_f32 v[162:163], v[162:163], v[162:163]
	s_nop 0
	v_pk_mul_f32 v[162:163], v[162:163], v[162:163]
	s_nop 0
	v_rcp_f32_e32 v162, v162
	v_rcp_f32_e32 v163, v163
	s_nop 0
	v_pk_fma_f32 v[126:127], v[154:155], v[162:163], v[126:127] neg_lo:[1,0,0] neg_hi:[1,0,0]
	v_and_b32_e32 v163, 0x7fffffff, v121
	v_and_b32_e32 v162, 0x7fffffff, v120
	v_pk_fma_f32 v[164:165], v[162:163], s[94:95], v[152:153] op_sel_hi:[1,0,0]
	v_max_f32_e32 v120, v120, v120
	v_pk_fma_f32 v[164:165], v[162:163], v[164:165], s[96:97] op_sel_hi:[1,1,0]
	v_max_f32_e32 v121, v121, v121
	v_pk_fma_f32 v[164:165], v[162:163], v[164:165], s[98:99] op_sel_hi:[1,1,0]
	v_and_b32_e32 v155, 0x7fffffff, v123
	v_pk_fma_f32 v[164:165], v[162:163], v[164:165], s[40:41] op_sel_hi:[1,1,0]
	v_and_b32_e32 v154, 0x7fffffff, v122
	v_pk_fma_f32 v[164:165], v[162:163], v[164:165], s[74:75] op_sel_hi:[1,1,0]
	v_max_f32_e32 v120, 0, v120
	v_pk_fma_f32 v[164:165], v[162:163], v[164:165], s[76:77] op_sel_hi:[1,1,0]
	v_max_f32_e32 v121, 0, v121
	v_pk_mul_f32 v[164:165], v[164:165], v[164:165]
	v_max_f32_e32 v122, v122, v122
	v_pk_mul_f32 v[164:165], v[164:165], v[164:165]
	v_max_f32_e32 v123, v123, v123
	v_pk_mul_f32 v[164:165], v[164:165], v[164:165]
	v_max_f32_e32 v122, 0, v122
	v_pk_mul_f32 v[164:165], v[164:165], v[164:165]
	v_max_f32_e32 v123, 0, v123
	v_rcp_f32_e32 v164, v164
	v_rcp_f32_e32 v165, v165
	s_nop 0
	v_pk_fma_f32 v[120:121], v[162:163], v[164:165], v[120:121] neg_lo:[1,0,0] neg_hi:[1,0,0]
	v_pk_fma_f32 v[162:163], v[154:155], s[94:95], v[152:153] op_sel_hi:[1,0,0]
	s_nop 0
	v_pk_fma_f32 v[162:163], v[154:155], v[162:163], s[96:97] op_sel_hi:[1,1,0]
	s_nop 0
	v_pk_fma_f32 v[162:163], v[154:155], v[162:163], s[98:99] op_sel_hi:[1,1,0]
	s_nop 0
	v_pk_fma_f32 v[162:163], v[154:155], v[162:163], s[40:41] op_sel_hi:[1,1,0]
	s_nop 0
	v_pk_fma_f32 v[162:163], v[154:155], v[162:163], s[74:75] op_sel_hi:[1,1,0]
	s_nop 0
	v_pk_fma_f32 v[162:163], v[154:155], v[162:163], s[76:77] op_sel_hi:[1,1,0]
	s_nop 0
	v_pk_mul_f32 v[162:163], v[162:163], v[162:163]
	s_nop 0
	v_pk_mul_f32 v[162:163], v[162:163], v[162:163]
	s_nop 0
	v_pk_mul_f32 v[162:163], v[162:163], v[162:163]
	s_nop 0
	v_pk_mul_f32 v[162:163], v[162:163], v[162:163]
	s_nop 0
	v_rcp_f32_e32 v162, v162
	v_rcp_f32_e32 v163, v163
	s_nop 0
	v_pk_fma_f32 v[122:123], v[154:155], v[162:163], v[122:123] neg_lo:[1,0,0] neg_hi:[1,0,0]
	v_mov_b32_e32 v155, s13
	v_or_b32_e32 v154, s12, v138
	v_lshlrev_b64 v[154:155], 10, v[154:155]
	v_cvt_pk_bf16_f32 v162, v124, v125
	v_cvt_pk_bf16_f32 v163, v126, v127
	v_cvt_pk_bf16_f32 v164, v120, v121
	v_cvt_pk_bf16_f32 v165, v122, v123
	v_lshl_add_u64 v[154:155], v[142:143], 0, v[154:155]
	global_store_dwordx4 v[154:155], v[162:165], off sc1
	s_or_b32 s12, s82, 1
	s_ashr_i32 s13, s12, 31
	v_and_b32_e32 v165, 0x7fffffff, v117
	v_and_b32_e32 v164, 0x7fffffff, v116
	v_pk_fma_f32 v[166:167], v[164:165], s[94:95], v[152:153] op_sel_hi:[1,0,0]
	v_max_f32_e32 v116, v116, v116
	v_pk_fma_f32 v[166:167], v[164:165], v[166:167], s[96:97] op_sel_hi:[1,1,0]
	v_max_f32_e32 v117, v117, v117
	v_pk_fma_f32 v[166:167], v[164:165], v[166:167], s[98:99] op_sel_hi:[1,1,0]
	v_and_b32_e32 v163, 0x7fffffff, v119
	v_pk_fma_f32 v[166:167], v[164:165], v[166:167], s[40:41] op_sel_hi:[1,1,0]
	v_and_b32_e32 v162, 0x7fffffff, v118
	v_pk_fma_f32 v[166:167], v[164:165], v[166:167], s[74:75] op_sel_hi:[1,1,0]
	v_max_f32_e32 v116, 0, v116
	v_pk_fma_f32 v[166:167], v[164:165], v[166:167], s[76:77] op_sel_hi:[1,1,0]
	v_max_f32_e32 v117, 0, v117
	v_pk_mul_f32 v[166:167], v[166:167], v[166:167]
	v_max_f32_e32 v118, v118, v118
	v_pk_mul_f32 v[166:167], v[166:167], v[166:167]
	v_max_f32_e32 v119, v119, v119
	v_pk_mul_f32 v[166:167], v[166:167], v[166:167]
	v_max_f32_e32 v118, 0, v118
	v_pk_mul_f32 v[166:167], v[166:167], v[166:167]
	v_max_f32_e32 v119, 0, v119
	v_rcp_f32_e32 v166, v166
	v_rcp_f32_e32 v167, v167
	s_lshl_b64 s[82:83], s[12:13], 8
	s_add_u32 s1, s82, s1
	s_addc_u32 s11, s83, s11
	v_pk_fma_f32 v[116:117], v[164:165], v[166:167], v[116:117] neg_lo:[1,0,0] neg_hi:[1,0,0]
	v_pk_fma_f32 v[164:165], v[162:163], s[94:95], v[152:153] op_sel_hi:[1,0,0]
	s_nop 0
	v_pk_fma_f32 v[164:165], v[162:163], v[164:165], s[96:97] op_sel_hi:[1,1,0]
	s_nop 0
	v_pk_fma_f32 v[164:165], v[162:163], v[164:165], s[98:99] op_sel_hi:[1,1,0]
	s_nop 0
	v_pk_fma_f32 v[164:165], v[162:163], v[164:165], s[40:41] op_sel_hi:[1,1,0]
	s_nop 0
	v_pk_fma_f32 v[164:165], v[162:163], v[164:165], s[74:75] op_sel_hi:[1,1,0]
	s_nop 0
	v_pk_fma_f32 v[164:165], v[162:163], v[164:165], s[76:77] op_sel_hi:[1,1,0]
	s_nop 0
	v_pk_mul_f32 v[164:165], v[164:165], v[164:165]
	s_nop 0
	v_pk_mul_f32 v[164:165], v[164:165], v[164:165]
	s_nop 0
	v_pk_mul_f32 v[164:165], v[164:165], v[164:165]
	s_nop 0
	v_pk_mul_f32 v[164:165], v[164:165], v[164:165]
	s_nop 0
	v_rcp_f32_e32 v164, v164
	v_rcp_f32_e32 v165, v165
	s_nop 0
	v_pk_fma_f32 v[118:119], v[162:163], v[164:165], v[118:119] neg_lo:[1,0,0] neg_hi:[1,0,0]
	v_and_b32_e32 v165, 0x7fffffff, v113
	v_and_b32_e32 v164, 0x7fffffff, v112
	v_pk_fma_f32 v[166:167], v[164:165], s[94:95], v[152:153] op_sel_hi:[1,0,0]
	v_max_f32_e32 v112, v112, v112
	v_pk_fma_f32 v[166:167], v[164:165], v[166:167], s[96:97] op_sel_hi:[1,1,0]
	v_max_f32_e32 v113, v113, v113
	v_pk_fma_f32 v[166:167], v[164:165], v[166:167], s[98:99] op_sel_hi:[1,1,0]
	v_and_b32_e32 v163, 0x7fffffff, v115
	v_pk_fma_f32 v[166:167], v[164:165], v[166:167], s[40:41] op_sel_hi:[1,1,0]
	v_and_b32_e32 v162, 0x7fffffff, v114
	v_pk_fma_f32 v[166:167], v[164:165], v[166:167], s[74:75] op_sel_hi:[1,1,0]
	v_max_f32_e32 v112, 0, v112
	v_pk_fma_f32 v[166:167], v[164:165], v[166:167], s[76:77] op_sel_hi:[1,1,0]
	v_max_f32_e32 v113, 0, v113
	v_pk_mul_f32 v[166:167], v[166:167], v[166:167]
	v_max_f32_e32 v114, v114, v114
	v_pk_mul_f32 v[166:167], v[166:167], v[166:167]
	v_max_f32_e32 v115, v115, v115
	v_pk_mul_f32 v[166:167], v[166:167], v[166:167]
	v_max_f32_e32 v114, 0, v114
	v_pk_mul_f32 v[166:167], v[166:167], v[166:167]
	v_max_f32_e32 v115, 0, v115
	v_rcp_f32_e32 v166, v166
	v_rcp_f32_e32 v167, v167
	s_nop 0
	v_pk_fma_f32 v[112:113], v[164:165], v[166:167], v[112:113] neg_lo:[1,0,0] neg_hi:[1,0,0]
	v_pk_fma_f32 v[164:165], v[162:163], s[94:95], v[152:153] op_sel_hi:[1,0,0]
	v_mov_b32_e32 v167, s11
	v_pk_fma_f32 v[164:165], v[162:163], v[164:165], s[96:97] op_sel_hi:[1,1,0]
	v_or_b32_e32 v166, s1, v138
	v_pk_fma_f32 v[164:165], v[162:163], v[164:165], s[98:99] op_sel_hi:[1,1,0]
	v_lshlrev_b64 v[166:167], 10, v[166:167]
	v_pk_fma_f32 v[164:165], v[162:163], v[164:165], s[40:41] op_sel_hi:[1,1,0]
	v_lshl_add_u64 v[166:167], v[142:143], 0, v[166:167]
	v_pk_fma_f32 v[164:165], v[162:163], v[164:165], s[74:75] op_sel_hi:[1,1,0]
	s_add_u32 s1, s4, s6
	v_pk_fma_f32 v[164:165], v[162:163], v[164:165], s[76:77] op_sel_hi:[1,1,0]
	s_addc_u32 s4, s5, 0
	v_pk_mul_f32 v[164:165], v[164:165], v[164:165]
	s_add_u32 s5, vcc_lo, s1
	v_pk_mul_f32 v[164:165], v[164:165], v[164:165]
	s_addc_u32 s11, vcc_hi, s4
	v_pk_mul_f32 v[164:165], v[164:165], v[164:165]
	s_add_u32 s1, s82, s1
	v_pk_mul_f32 v[164:165], v[164:165], v[164:165]
	s_addc_u32 s4, s83, s4
	v_rcp_f32_e32 v164, v164
	v_rcp_f32_e32 v165, v165
	s_or_b32 s0, s0, 1
	v_pk_fma_f32 v[114:115], v[162:163], v[164:165], v[114:115] neg_lo:[1,0,0] neg_hi:[1,0,0]
	v_cvt_pk_bf16_f32 v162, v116, v117
	v_cvt_pk_bf16_f32 v163, v118, v119
	v_cvt_pk_bf16_f32 v164, v112, v113
	s_nop 0
	v_cvt_pk_bf16_f32 v165, v114, v115
	global_store_dwordx4 v[166:167], v[162:165], off sc1
	s_nop 1
	v_and_b32_e32 v165, 0x7fffffff, v109
	v_and_b32_e32 v164, 0x7fffffff, v108
	v_pk_fma_f32 v[168:169], v[164:165], s[94:95], v[152:153] op_sel_hi:[1,0,0]
	v_max_f32_e32 v108, v108, v108
	v_pk_fma_f32 v[168:169], v[164:165], v[168:169], s[96:97] op_sel_hi:[1,1,0]
	v_max_f32_e32 v109, v109, v109
	v_pk_fma_f32 v[168:169], v[164:165], v[168:169], s[98:99] op_sel_hi:[1,1,0]
	v_and_b32_e32 v163, 0x7fffffff, v111
	v_pk_fma_f32 v[168:169], v[164:165], v[168:169], s[40:41] op_sel_hi:[1,1,0]
	v_and_b32_e32 v162, 0x7fffffff, v110
	v_pk_fma_f32 v[168:169], v[164:165], v[168:169], s[74:75] op_sel_hi:[1,1,0]
	v_max_f32_e32 v108, 0, v108
	v_pk_fma_f32 v[168:169], v[164:165], v[168:169], s[76:77] op_sel_hi:[1,1,0]
	v_max_f32_e32 v109, 0, v109
	v_pk_mul_f32 v[168:169], v[168:169], v[168:169]
	v_max_f32_e32 v110, v110, v110
	v_pk_mul_f32 v[168:169], v[168:169], v[168:169]
	v_max_f32_e32 v111, v111, v111
	v_pk_mul_f32 v[168:169], v[168:169], v[168:169]
	v_max_f32_e32 v110, 0, v110
	v_pk_mul_f32 v[168:169], v[168:169], v[168:169]
	v_max_f32_e32 v111, 0, v111
	v_rcp_f32_e32 v168, v168
	v_rcp_f32_e32 v169, v169
	s_nop 0
	v_pk_fma_f32 v[108:109], v[164:165], v[168:169], v[108:109] neg_lo:[1,0,0] neg_hi:[1,0,0]
	v_pk_fma_f32 v[164:165], v[162:163], s[94:95], v[152:153] op_sel_hi:[1,0,0]
	s_nop 0
	v_pk_fma_f32 v[164:165], v[162:163], v[164:165], s[96:97] op_sel_hi:[1,1,0]
	s_nop 0
	v_pk_fma_f32 v[164:165], v[162:163], v[164:165], s[98:99] op_sel_hi:[1,1,0]
	s_nop 0
	v_pk_fma_f32 v[164:165], v[162:163], v[164:165], s[40:41] op_sel_hi:[1,1,0]
	s_nop 0
	v_pk_fma_f32 v[164:165], v[162:163], v[164:165], s[74:75] op_sel_hi:[1,1,0]
	s_nop 0
	v_pk_fma_f32 v[164:165], v[162:163], v[164:165], s[76:77] op_sel_hi:[1,1,0]
	s_nop 0
	v_pk_mul_f32 v[164:165], v[164:165], v[164:165]
	s_nop 0
	v_pk_mul_f32 v[164:165], v[164:165], v[164:165]
	s_nop 0
	v_pk_mul_f32 v[164:165], v[164:165], v[164:165]
	s_nop 0
	v_pk_mul_f32 v[164:165], v[164:165], v[164:165]
	s_nop 0
	v_rcp_f32_e32 v164, v164
	v_rcp_f32_e32 v165, v165
	s_nop 0
	v_pk_fma_f32 v[110:111], v[162:163], v[164:165], v[110:111] neg_lo:[1,0,0] neg_hi:[1,0,0]
	v_and_b32_e32 v165, 0x7fffffff, v105
	v_and_b32_e32 v164, 0x7fffffff, v104
	v_pk_fma_f32 v[168:169], v[164:165], s[94:95], v[152:153] op_sel_hi:[1,0,0]
	v_max_f32_e32 v104, v104, v104
	v_pk_fma_f32 v[168:169], v[164:165], v[168:169], s[96:97] op_sel_hi:[1,1,0]
	v_max_f32_e32 v105, v105, v105
	v_pk_fma_f32 v[168:169], v[164:165], v[168:169], s[98:99] op_sel_hi:[1,1,0]
	v_and_b32_e32 v163, 0x7fffffff, v107
	v_pk_fma_f32 v[168:169], v[164:165], v[168:169], s[40:41] op_sel_hi:[1,1,0]
	v_and_b32_e32 v162, 0x7fffffff, v106
	v_pk_fma_f32 v[168:169], v[164:165], v[168:169], s[74:75] op_sel_hi:[1,1,0]
	v_max_f32_e32 v104, 0, v104
	v_pk_fma_f32 v[168:169], v[164:165], v[168:169], s[76:77] op_sel_hi:[1,1,0]
	v_max_f32_e32 v105, 0, v105
	v_pk_mul_f32 v[168:169], v[168:169], v[168:169]
	v_max_f32_e32 v106, v106, v106
	v_pk_mul_f32 v[168:169], v[168:169], v[168:169]
	v_max_f32_e32 v107, v107, v107
	v_pk_mul_f32 v[168:169], v[168:169], v[168:169]
	v_max_f32_e32 v106, 0, v106
	v_pk_mul_f32 v[168:169], v[168:169], v[168:169]
	v_max_f32_e32 v107, 0, v107
	v_rcp_f32_e32 v168, v168
	v_rcp_f32_e32 v169, v169
	s_nop 0
	v_pk_fma_f32 v[164:165], v[164:165], v[168:169], v[104:105] neg_lo:[1,0,0] neg_hi:[1,0,0]
	v_pk_fma_f32 v[104:105], v[162:163], s[94:95], v[152:153] op_sel_hi:[1,0,0]
	s_nop 0
	v_pk_fma_f32 v[104:105], v[162:163], v[104:105], s[96:97] op_sel_hi:[1,1,0]
	s_nop 0
	v_pk_fma_f32 v[104:105], v[162:163], v[104:105], s[98:99] op_sel_hi:[1,1,0]
	s_nop 0
	v_pk_fma_f32 v[104:105], v[162:163], v[104:105], s[40:41] op_sel_hi:[1,1,0]
	s_nop 0
	v_pk_fma_f32 v[104:105], v[162:163], v[104:105], s[74:75] op_sel_hi:[1,1,0]
	s_nop 0
	v_pk_fma_f32 v[104:105], v[162:163], v[104:105], s[76:77] op_sel_hi:[1,1,0]
	s_nop 0
	v_pk_mul_f32 v[104:105], v[104:105], v[104:105]
	s_nop 0
	v_pk_mul_f32 v[104:105], v[104:105], v[104:105]
	s_nop 0
	v_pk_mul_f32 v[104:105], v[104:105], v[104:105]
	s_nop 0
	v_pk_mul_f32 v[104:105], v[104:105], v[104:105]
	s_nop 0
	v_rcp_f32_e32 v104, v104
	v_rcp_f32_e32 v105, v105
	s_nop 0
	v_pk_fma_f32 v[162:163], v[162:163], v[104:105], v[106:107] neg_lo:[1,0,0] neg_hi:[1,0,0]
	v_pk_mul_f32 v[104:105], v[108:109], v[108:109]
	s_nop 0
	v_pk_fma_f32 v[124:125], v[124:125], v[124:125], v[104:105]
	v_pk_mul_f32 v[104:105], v[164:165], v[164:165]
	s_nop 0
	v_pk_fma_f32 v[120:121], v[120:121], v[120:121], v[104:105]
	v_pk_mul_f32 v[104:105], v[110:111], v[110:111]
	s_nop 0
	v_pk_fma_f32 v[126:127], v[126:127], v[126:127], v[104:105]
	v_pk_mul_f32 v[104:105], v[162:163], v[162:163]
	s_nop 0
	v_pk_fma_f32 v[122:123], v[122:123], v[122:123], v[104:105]
	v_cvt_pk_bf16_f32 v104, v108, v109
	v_cvt_pk_bf16_f32 v105, v110, v111
	v_cvt_pk_bf16_f32 v106, v164, v165
	v_cvt_pk_bf16_f32 v107, v162, v163
	global_store_dwordx4 v[154:155], v[104:107], off offset:128 sc1
	s_nop 1
	v_and_b32_e32 v107, 0x7fffffff, v101
	v_and_b32_e32 v106, 0x7fffffff, v100
	v_pk_fma_f32 v[108:109], v[106:107], s[94:95], v[152:153] op_sel_hi:[1,0,0]
	v_max_f32_e32 v100, v100, v100
	v_pk_fma_f32 v[108:109], v[106:107], v[108:109], s[96:97] op_sel_hi:[1,1,0]
	v_max_f32_e32 v101, v101, v101
	v_pk_fma_f32 v[108:109], v[106:107], v[108:109], s[98:99] op_sel_hi:[1,1,0]
	v_and_b32_e32 v105, 0x7fffffff, v103
	v_pk_fma_f32 v[108:109], v[106:107], v[108:109], s[40:41] op_sel_hi:[1,1,0]
	v_and_b32_e32 v104, 0x7fffffff, v102
	v_pk_fma_f32 v[108:109], v[106:107], v[108:109], s[74:75] op_sel_hi:[1,1,0]
	v_max_f32_e32 v100, 0, v100
	v_pk_fma_f32 v[108:109], v[106:107], v[108:109], s[76:77] op_sel_hi:[1,1,0]
	v_max_f32_e32 v101, 0, v101
	v_pk_mul_f32 v[108:109], v[108:109], v[108:109]
	v_max_f32_e32 v102, v102, v102
	v_pk_mul_f32 v[108:109], v[108:109], v[108:109]
	v_max_f32_e32 v103, v103, v103
	v_pk_mul_f32 v[108:109], v[108:109], v[108:109]
	v_max_f32_e32 v102, 0, v102
	v_pk_mul_f32 v[108:109], v[108:109], v[108:109]
	v_max_f32_e32 v103, 0, v103
	v_rcp_f32_e32 v108, v108
	v_rcp_f32_e32 v109, v109
	s_nop 0
	v_pk_fma_f32 v[100:101], v[106:107], v[108:109], v[100:101] neg_lo:[1,0,0] neg_hi:[1,0,0]
	v_pk_fma_f32 v[106:107], v[104:105], s[94:95], v[152:153] op_sel_hi:[1,0,0]
	s_nop 0
	v_pk_fma_f32 v[106:107], v[104:105], v[106:107], s[96:97] op_sel_hi:[1,1,0]
	s_nop 0
	v_pk_fma_f32 v[106:107], v[104:105], v[106:107], s[98:99] op_sel_hi:[1,1,0]
	s_nop 0
	v_pk_fma_f32 v[106:107], v[104:105], v[106:107], s[40:41] op_sel_hi:[1,1,0]
	s_nop 0
	v_pk_fma_f32 v[106:107], v[104:105], v[106:107], s[74:75] op_sel_hi:[1,1,0]
	s_nop 0
	v_pk_fma_f32 v[106:107], v[104:105], v[106:107], s[76:77] op_sel_hi:[1,1,0]
	s_nop 0
	v_pk_mul_f32 v[106:107], v[106:107], v[106:107]
	s_nop 0
	v_pk_mul_f32 v[106:107], v[106:107], v[106:107]
	s_nop 0
	v_pk_mul_f32 v[106:107], v[106:107], v[106:107]
	s_nop 0
	v_pk_mul_f32 v[106:107], v[106:107], v[106:107]
	s_nop 0
	v_rcp_f32_e32 v106, v106
	v_rcp_f32_e32 v107, v107
	s_nop 0
	v_pk_fma_f32 v[102:103], v[104:105], v[106:107], v[102:103] neg_lo:[1,0,0] neg_hi:[1,0,0]
	v_and_b32_e32 v107, 0x7fffffff, v97
	v_and_b32_e32 v106, 0x7fffffff, v96
	v_pk_fma_f32 v[108:109], v[106:107], s[94:95], v[152:153] op_sel_hi:[1,0,0]
	v_max_f32_e32 v96, v96, v96
	v_pk_fma_f32 v[108:109], v[106:107], v[108:109], s[96:97] op_sel_hi:[1,1,0]
	v_max_f32_e32 v97, v97, v97
	v_pk_fma_f32 v[108:109], v[106:107], v[108:109], s[98:99] op_sel_hi:[1,1,0]
	v_and_b32_e32 v105, 0x7fffffff, v99
	v_pk_fma_f32 v[108:109], v[106:107], v[108:109], s[40:41] op_sel_hi:[1,1,0]
	v_and_b32_e32 v104, 0x7fffffff, v98
	v_pk_fma_f32 v[108:109], v[106:107], v[108:109], s[74:75] op_sel_hi:[1,1,0]
	v_max_f32_e32 v96, 0, v96
	v_pk_fma_f32 v[108:109], v[106:107], v[108:109], s[76:77] op_sel_hi:[1,1,0]
	v_max_f32_e32 v97, 0, v97
	v_pk_mul_f32 v[108:109], v[108:109], v[108:109]
	v_max_f32_e32 v98, v98, v98
	v_pk_mul_f32 v[108:109], v[108:109], v[108:109]
	v_max_f32_e32 v99, v99, v99
	v_pk_mul_f32 v[108:109], v[108:109], v[108:109]
	v_max_f32_e32 v98, 0, v98
	v_pk_mul_f32 v[108:109], v[108:109], v[108:109]
	v_max_f32_e32 v99, 0, v99
	v_rcp_f32_e32 v108, v108
	v_rcp_f32_e32 v109, v109
	s_nop 0
	v_pk_fma_f32 v[106:107], v[106:107], v[108:109], v[96:97] neg_lo:[1,0,0] neg_hi:[1,0,0]
	v_pk_fma_f32 v[96:97], v[104:105], s[94:95], v[152:153] op_sel_hi:[1,0,0]
	s_nop 0
	v_pk_fma_f32 v[96:97], v[104:105], v[96:97], s[96:97] op_sel_hi:[1,1,0]
	s_nop 0
	v_pk_fma_f32 v[96:97], v[104:105], v[96:97], s[98:99] op_sel_hi:[1,1,0]
	s_nop 0
	v_pk_fma_f32 v[96:97], v[104:105], v[96:97], s[40:41] op_sel_hi:[1,1,0]
	s_nop 0
	v_pk_fma_f32 v[96:97], v[104:105], v[96:97], s[74:75] op_sel_hi:[1,1,0]
	s_nop 0
	v_pk_fma_f32 v[96:97], v[104:105], v[96:97], s[76:77] op_sel_hi:[1,1,0]
	s_nop 0
	v_pk_mul_f32 v[96:97], v[96:97], v[96:97]
	s_nop 0
	v_pk_mul_f32 v[96:97], v[96:97], v[96:97]
	s_nop 0
	v_pk_mul_f32 v[96:97], v[96:97], v[96:97]
	s_nop 0
	v_pk_mul_f32 v[96:97], v[96:97], v[96:97]
	s_nop 0
	v_rcp_f32_e32 v96, v96
	v_rcp_f32_e32 v97, v97
	s_nop 0
	v_pk_fma_f32 v[104:105], v[104:105], v[96:97], v[98:99] neg_lo:[1,0,0] neg_hi:[1,0,0]
	v_pk_mul_f32 v[98:99], v[106:107], v[106:107]
	v_pk_mul_f32 v[96:97], v[100:101], v[100:101]
	v_pk_fma_f32 v[108:109], v[112:113], v[112:113], v[98:99]
	v_pk_mul_f32 v[98:99], v[102:103], v[102:103]
	v_pk_fma_f32 v[96:97], v[116:117], v[116:117], v[96:97]
	v_pk_fma_f32 v[110:111], v[118:119], v[118:119], v[98:99]
	v_pk_mul_f32 v[98:99], v[104:105], v[104:105]
	s_nop 0
	v_pk_fma_f32 v[112:113], v[114:115], v[114:115], v[98:99]
	v_cvt_pk_bf16_f32 v98, v100, v101
	v_cvt_pk_bf16_f32 v99, v102, v103
	v_cvt_pk_bf16_f32 v100, v106, v107
	v_cvt_pk_bf16_f32 v101, v104, v105
	global_store_dwordx4 v[166:167], v[98:101], off offset:128 sc1
	s_nop 1
	v_and_b32_e32 v101, 0x7fffffff, v93
	v_and_b32_e32 v100, 0x7fffffff, v92
	v_pk_fma_f32 v[102:103], v[100:101], s[94:95], v[152:153] op_sel_hi:[1,0,0]
	v_max_f32_e32 v92, v92, v92
	v_pk_fma_f32 v[102:103], v[100:101], v[102:103], s[96:97] op_sel_hi:[1,1,0]
	v_max_f32_e32 v93, v93, v93
	v_pk_fma_f32 v[102:103], v[100:101], v[102:103], s[98:99] op_sel_hi:[1,1,0]
	v_and_b32_e32 v99, 0x7fffffff, v95
	v_pk_fma_f32 v[102:103], v[100:101], v[102:103], s[40:41] op_sel_hi:[1,1,0]
	v_and_b32_e32 v98, 0x7fffffff, v94
	v_pk_fma_f32 v[102:103], v[100:101], v[102:103], s[74:75] op_sel_hi:[1,1,0]
	v_max_f32_e32 v92, 0, v92
	v_pk_fma_f32 v[102:103], v[100:101], v[102:103], s[76:77] op_sel_hi:[1,1,0]
	v_max_f32_e32 v93, 0, v93
	v_pk_mul_f32 v[102:103], v[102:103], v[102:103]
	v_max_f32_e32 v94, v94, v94
	v_pk_mul_f32 v[102:103], v[102:103], v[102:103]
	v_max_f32_e32 v95, v95, v95
	v_pk_mul_f32 v[102:103], v[102:103], v[102:103]
	v_max_f32_e32 v94, 0, v94
	v_pk_mul_f32 v[102:103], v[102:103], v[102:103]
	v_max_f32_e32 v95, 0, v95
	v_rcp_f32_e32 v102, v102
	v_rcp_f32_e32 v103, v103
	s_nop 0
	v_pk_fma_f32 v[100:101], v[100:101], v[102:103], v[92:93] neg_lo:[1,0,0] neg_hi:[1,0,0]
	v_pk_fma_f32 v[92:93], v[98:99], s[94:95], v[152:153] op_sel_hi:[1,0,0]
	s_nop 0
	v_pk_fma_f32 v[92:93], v[98:99], v[92:93], s[96:97] op_sel_hi:[1,1,0]
	s_nop 0
	v_pk_fma_f32 v[92:93], v[98:99], v[92:93], s[98:99] op_sel_hi:[1,1,0]
	s_nop 0
	v_pk_fma_f32 v[92:93], v[98:99], v[92:93], s[40:41] op_sel_hi:[1,1,0]
	s_nop 0
	v_pk_fma_f32 v[92:93], v[98:99], v[92:93], s[74:75] op_sel_hi:[1,1,0]
	s_nop 0
	v_pk_fma_f32 v[92:93], v[98:99], v[92:93], s[76:77] op_sel_hi:[1,1,0]
	s_nop 0
	v_pk_mul_f32 v[92:93], v[92:93], v[92:93]
	s_nop 0
	v_pk_mul_f32 v[92:93], v[92:93], v[92:93]
	s_nop 0
	v_pk_mul_f32 v[92:93], v[92:93], v[92:93]
	s_nop 0
	v_pk_mul_f32 v[92:93], v[92:93], v[92:93]
	s_nop 0
	v_rcp_f32_e32 v92, v92
	v_rcp_f32_e32 v93, v93
	s_nop 0
	v_pk_fma_f32 v[102:103], v[98:99], v[92:93], v[94:95] neg_lo:[1,0,0] neg_hi:[1,0,0]
	v_and_b32_e32 v95, 0x7fffffff, v89
	v_and_b32_e32 v94, 0x7fffffff, v88
	v_pk_fma_f32 v[98:99], v[94:95], s[94:95], v[152:153] op_sel_hi:[1,0,0]
	v_max_f32_e32 v88, v88, v88
	v_pk_fma_f32 v[98:99], v[94:95], v[98:99], s[96:97] op_sel_hi:[1,1,0]
	v_max_f32_e32 v89, v89, v89
	v_pk_fma_f32 v[98:99], v[94:95], v[98:99], s[98:99] op_sel_hi:[1,1,0]
	v_and_b32_e32 v93, 0x7fffffff, v91
	v_pk_fma_f32 v[98:99], v[94:95], v[98:99], s[40:41] op_sel_hi:[1,1,0]
	v_and_b32_e32 v92, 0x7fffffff, v90
	v_pk_fma_f32 v[98:99], v[94:95], v[98:99], s[74:75] op_sel_hi:[1,1,0]
	v_max_f32_e32 v88, 0, v88
	v_pk_fma_f32 v[98:99], v[94:95], v[98:99], s[76:77] op_sel_hi:[1,1,0]
	v_max_f32_e32 v89, 0, v89
	v_pk_mul_f32 v[98:99], v[98:99], v[98:99]
	v_max_f32_e32 v90, v90, v90
	v_pk_mul_f32 v[98:99], v[98:99], v[98:99]
	v_max_f32_e32 v91, v91, v91
	v_pk_mul_f32 v[98:99], v[98:99], v[98:99]
	v_max_f32_e32 v90, 0, v90
	v_pk_mul_f32 v[98:99], v[98:99], v[98:99]
	v_max_f32_e32 v91, 0, v91
	v_rcp_f32_e32 v98, v98
	v_rcp_f32_e32 v99, v99
	s_nop 0
	v_pk_fma_f32 v[104:105], v[94:95], v[98:99], v[88:89] neg_lo:[1,0,0] neg_hi:[1,0,0]
	v_pk_fma_f32 v[88:89], v[92:93], s[94:95], v[152:153] op_sel_hi:[1,0,0]
	v_cvt_pk_bf16_f32 v98, v100, v101
	v_cvt_pk_bf16_f32 v99, v102, v103
	s_nop 0
	v_pk_fma_f32 v[88:89], v[92:93], v[88:89], s[96:97] op_sel_hi:[1,1,0]
	s_nop 0
	v_pk_fma_f32 v[88:89], v[92:93], v[88:89], s[98:99] op_sel_hi:[1,1,0]
	s_nop 0
	v_pk_fma_f32 v[88:89], v[92:93], v[88:89], s[40:41] op_sel_hi:[1,1,0]
	s_nop 0
	v_pk_fma_f32 v[88:89], v[92:93], v[88:89], s[74:75] op_sel_hi:[1,1,0]
	s_nop 0
	v_pk_fma_f32 v[88:89], v[92:93], v[88:89], s[76:77] op_sel_hi:[1,1,0]
	s_nop 0
	v_pk_mul_f32 v[88:89], v[88:89], v[88:89]
	s_nop 0
	v_pk_mul_f32 v[88:89], v[88:89], v[88:89]
	s_nop 0
	v_pk_mul_f32 v[88:89], v[88:89], v[88:89]
	s_nop 0
	v_pk_mul_f32 v[88:89], v[88:89], v[88:89]
	s_nop 0
	v_rcp_f32_e32 v88, v88
	v_rcp_f32_e32 v89, v89
	s_nop 0
	v_pk_fma_f32 v[106:107], v[92:93], v[88:89], v[90:91] neg_lo:[1,0,0] neg_hi:[1,0,0]
	v_pk_fma_f32 v[92:93], v[102:103], v[102:103], v[126:127]
	v_mov_b32_e32 v103, s11
	v_or_b32_e32 v102, s5, v138
	v_lshlrev_b64 v[102:103], 10, v[102:103]
	v_pk_fma_f32 v[88:89], v[100:101], v[100:101], v[124:125]
	v_cvt_pk_bf16_f32 v100, v104, v105
	v_cvt_pk_bf16_f32 v101, v106, v107
	v_lshl_add_u64 v[102:103], v[142:143], 0, v[102:103]
	global_store_dwordx4 v[102:103], v[98:101], off sc1
	v_pk_fma_f32 v[90:91], v[104:105], v[104:105], v[120:121]
	v_pk_fma_f32 v[94:95], v[106:107], v[106:107], v[122:123]
	v_and_b32_e32 v101, 0x7fffffff, v85
	v_and_b32_e32 v100, 0x7fffffff, v84
	v_pk_fma_f32 v[104:105], v[100:101], s[94:95], v[152:153] op_sel_hi:[1,0,0]
	v_max_f32_e32 v84, v84, v84
	v_pk_fma_f32 v[104:105], v[100:101], v[104:105], s[96:97] op_sel_hi:[1,1,0]
	v_max_f32_e32 v85, v85, v85
	v_pk_fma_f32 v[104:105], v[100:101], v[104:105], s[98:99] op_sel_hi:[1,1,0]
	v_and_b32_e32 v99, 0x7fffffff, v87
	v_pk_fma_f32 v[104:105], v[100:101], v[104:105], s[40:41] op_sel_hi:[1,1,0]
	v_and_b32_e32 v98, 0x7fffffff, v86
	v_pk_fma_f32 v[104:105], v[100:101], v[104:105], s[74:75] op_sel_hi:[1,1,0]
	v_max_f32_e32 v84, 0, v84
	v_pk_fma_f32 v[104:105], v[100:101], v[104:105], s[76:77] op_sel_hi:[1,1,0]
	v_max_f32_e32 v85, 0, v85
	v_pk_mul_f32 v[104:105], v[104:105], v[104:105]
	v_max_f32_e32 v86, v86, v86
	v_pk_mul_f32 v[104:105], v[104:105], v[104:105]
	v_max_f32_e32 v87, v87, v87
	v_pk_mul_f32 v[104:105], v[104:105], v[104:105]
	v_max_f32_e32 v86, 0, v86
	v_pk_mul_f32 v[104:105], v[104:105], v[104:105]
	v_max_f32_e32 v87, 0, v87
	v_rcp_f32_e32 v104, v104
	v_rcp_f32_e32 v105, v105
	s_nop 0
	v_pk_fma_f32 v[84:85], v[100:101], v[104:105], v[84:85] neg_lo:[1,0,0] neg_hi:[1,0,0]
	v_pk_fma_f32 v[100:101], v[98:99], s[94:95], v[152:153] op_sel_hi:[1,0,0]
	v_pk_fma_f32 v[96:97], v[84:85], v[84:85], v[96:97]
	v_pk_fma_f32 v[100:101], v[98:99], v[100:101], s[96:97] op_sel_hi:[1,1,0]
	s_nop 0
	v_pk_fma_f32 v[100:101], v[98:99], v[100:101], s[98:99] op_sel_hi:[1,1,0]
	s_nop 0
	v_pk_fma_f32 v[100:101], v[98:99], v[100:101], s[40:41] op_sel_hi:[1,1,0]
	s_nop 0
	v_pk_fma_f32 v[100:101], v[98:99], v[100:101], s[74:75] op_sel_hi:[1,1,0]
	s_nop 0
	v_pk_fma_f32 v[100:101], v[98:99], v[100:101], s[76:77] op_sel_hi:[1,1,0]
	s_nop 0
	v_pk_mul_f32 v[100:101], v[100:101], v[100:101]
	s_nop 0
	v_pk_mul_f32 v[100:101], v[100:101], v[100:101]
	s_nop 0
	v_pk_mul_f32 v[100:101], v[100:101], v[100:101]
	s_nop 0
	v_pk_mul_f32 v[100:101], v[100:101], v[100:101]
	s_nop 0
	v_rcp_f32_e32 v100, v100
	v_rcp_f32_e32 v101, v101
	s_nop 0
	v_pk_fma_f32 v[86:87], v[98:99], v[100:101], v[86:87] neg_lo:[1,0,0] neg_hi:[1,0,0]
	v_and_b32_e32 v101, 0x7fffffff, v81
	v_and_b32_e32 v100, 0x7fffffff, v80
	v_pk_fma_f32 v[104:105], v[100:101], s[94:95], v[152:153] op_sel_hi:[1,0,0]
	v_max_f32_e32 v80, v80, v80
	v_pk_fma_f32 v[104:105], v[100:101], v[104:105], s[96:97] op_sel_hi:[1,1,0]
	v_max_f32_e32 v81, v81, v81
	v_pk_fma_f32 v[104:105], v[100:101], v[104:105], s[98:99] op_sel_hi:[1,1,0]
	v_and_b32_e32 v99, 0x7fffffff, v83
	v_pk_fma_f32 v[104:105], v[100:101], v[104:105], s[40:41] op_sel_hi:[1,1,0]
	v_and_b32_e32 v98, 0x7fffffff, v82
	v_pk_fma_f32 v[104:105], v[100:101], v[104:105], s[74:75] op_sel_hi:[1,1,0]
	v_max_f32_e32 v80, 0, v80
	v_pk_fma_f32 v[104:105], v[100:101], v[104:105], s[76:77] op_sel_hi:[1,1,0]
	v_max_f32_e32 v81, 0, v81
	v_pk_mul_f32 v[104:105], v[104:105], v[104:105]
	v_max_f32_e32 v82, v82, v82
	v_pk_mul_f32 v[104:105], v[104:105], v[104:105]
	v_max_f32_e32 v83, v83, v83
	v_pk_mul_f32 v[104:105], v[104:105], v[104:105]
	v_max_f32_e32 v82, 0, v82
	v_pk_mul_f32 v[104:105], v[104:105], v[104:105]
	v_max_f32_e32 v83, 0, v83
	v_rcp_f32_e32 v104, v104
	v_rcp_f32_e32 v105, v105
	v_pk_fma_f32 v[106:107], v[86:87], v[86:87], v[110:111]
	v_pk_fma_f32 v[100:101], v[100:101], v[104:105], v[80:81] neg_lo:[1,0,0] neg_hi:[1,0,0]
	v_pk_fma_f32 v[80:81], v[98:99], s[94:95], v[152:153] op_sel_hi:[1,0,0]
	v_pk_fma_f32 v[104:105], v[100:101], v[100:101], v[108:109]
	v_pk_fma_f32 v[80:81], v[98:99], v[80:81], s[96:97] op_sel_hi:[1,1,0]
	s_nop 0
	v_pk_fma_f32 v[80:81], v[98:99], v[80:81], s[98:99] op_sel_hi:[1,1,0]
	s_nop 0
	v_pk_fma_f32 v[80:81], v[98:99], v[80:81], s[40:41] op_sel_hi:[1,1,0]
	s_nop 0
	v_pk_fma_f32 v[80:81], v[98:99], v[80:81], s[74:75] op_sel_hi:[1,1,0]
	s_nop 0
	v_pk_fma_f32 v[80:81], v[98:99], v[80:81], s[76:77] op_sel_hi:[1,1,0]
	s_nop 0
	v_pk_mul_f32 v[80:81], v[80:81], v[80:81]
	s_nop 0
	v_pk_mul_f32 v[80:81], v[80:81], v[80:81]
	s_nop 0
	v_pk_mul_f32 v[80:81], v[80:81], v[80:81]
	s_nop 0
	v_pk_mul_f32 v[80:81], v[80:81], v[80:81]
	s_nop 0
	v_rcp_f32_e32 v80, v80
	v_rcp_f32_e32 v81, v81
	s_nop 0
	v_pk_fma_f32 v[98:99], v[98:99], v[80:81], v[82:83] neg_lo:[1,0,0] neg_hi:[1,0,0]
	v_cvt_pk_bf16_f32 v80, v84, v85
	v_mov_b32_e32 v85, s4
	v_or_b32_e32 v84, s1, v138
	v_lshlrev_b64 v[84:85], 10, v[84:85]
	v_cvt_pk_bf16_f32 v81, v86, v87
	v_cvt_pk_bf16_f32 v82, v100, v101
	v_cvt_pk_bf16_f32 v83, v98, v99
	v_lshl_add_u64 v[84:85], v[142:143], 0, v[84:85]
	global_store_dwordx4 v[84:85], v[80:83], off sc1
	s_ashr_i32 s1, s0, 31
	s_lshl_b64 s[0:1], s[0:1], 5
	v_and_b32_e32 v83, 0x7fffffff, v77
	v_and_b32_e32 v82, 0x7fffffff, v76
	v_pk_fma_f32 v[86:87], v[82:83], s[94:95], v[152:153] op_sel_hi:[1,0,0]
	v_max_f32_e32 v76, v76, v76
	v_pk_fma_f32 v[86:87], v[82:83], v[86:87], s[96:97] op_sel_hi:[1,1,0]
	v_max_f32_e32 v77, v77, v77
	v_pk_fma_f32 v[86:87], v[82:83], v[86:87], s[98:99] op_sel_hi:[1,1,0]
	v_and_b32_e32 v81, 0x7fffffff, v79
	v_pk_fma_f32 v[86:87], v[82:83], v[86:87], s[40:41] op_sel_hi:[1,1,0]
	v_and_b32_e32 v80, 0x7fffffff, v78
	v_pk_fma_f32 v[86:87], v[82:83], v[86:87], s[74:75] op_sel_hi:[1,1,0]
	v_max_f32_e32 v76, 0, v76
	v_pk_fma_f32 v[86:87], v[82:83], v[86:87], s[76:77] op_sel_hi:[1,1,0]
	v_max_f32_e32 v77, 0, v77
	v_pk_mul_f32 v[86:87], v[86:87], v[86:87]
	v_max_f32_e32 v78, v78, v78
	v_pk_mul_f32 v[86:87], v[86:87], v[86:87]
	v_max_f32_e32 v79, v79, v79
	v_pk_mul_f32 v[86:87], v[86:87], v[86:87]
	v_max_f32_e32 v78, 0, v78
	v_pk_mul_f32 v[86:87], v[86:87], v[86:87]
	v_max_f32_e32 v79, 0, v79
	v_rcp_f32_e32 v86, v86
	v_rcp_f32_e32 v87, v87
	s_add_u32 s4, s0, s41
	s_addc_u32 s5, s1, 0
	s_add_u32 s11, s4, vcc_lo
	v_pk_fma_f32 v[76:77], v[82:83], v[86:87], v[76:77] neg_lo:[1,0,0] neg_hi:[1,0,0]
	v_pk_fma_f32 v[82:83], v[80:81], s[94:95], v[152:153] op_sel_hi:[1,0,0]
	v_pk_fma_f32 v[108:109], v[98:99], v[98:99], v[112:113]
	v_pk_fma_f32 v[82:83], v[80:81], v[82:83], s[96:97] op_sel_hi:[1,1,0]
	s_addc_u32 s12, s5, vcc_hi
	v_pk_fma_f32 v[82:83], v[80:81], v[82:83], s[98:99] op_sel_hi:[1,1,0]
	s_add_u32 s4, s82, s4
	v_pk_fma_f32 v[82:83], v[80:81], v[82:83], s[40:41] op_sel_hi:[1,1,0]
	s_addc_u32 s5, s83, s5
	v_pk_fma_f32 v[82:83], v[80:81], v[82:83], s[74:75] op_sel_hi:[1,1,0]
	s_add_u32 s0, s0, s6
	v_pk_fma_f32 v[82:83], v[80:81], v[82:83], s[76:77] op_sel_hi:[1,1,0]
	s_addc_u32 s1, s1, 0
	v_pk_mul_f32 v[82:83], v[82:83], v[82:83]
	s_nop 0
	v_pk_mul_f32 v[82:83], v[82:83], v[82:83]
	s_nop 0
	v_pk_mul_f32 v[82:83], v[82:83], v[82:83]
	s_nop 0
	v_pk_mul_f32 v[82:83], v[82:83], v[82:83]
	s_nop 0
	v_rcp_f32_e32 v82, v82
	v_rcp_f32_e32 v83, v83
	s_nop 0
	v_pk_fma_f32 v[78:79], v[80:81], v[82:83], v[78:79] neg_lo:[1,0,0] neg_hi:[1,0,0]
	v_and_b32_e32 v83, 0x7fffffff, v73
	v_and_b32_e32 v82, 0x7fffffff, v72
	v_pk_fma_f32 v[86:87], v[82:83], s[94:95], v[152:153] op_sel_hi:[1,0,0]
	v_max_f32_e32 v72, v72, v72
	v_pk_fma_f32 v[86:87], v[82:83], v[86:87], s[96:97] op_sel_hi:[1,1,0]
	v_max_f32_e32 v73, v73, v73
	v_pk_fma_f32 v[86:87], v[82:83], v[86:87], s[98:99] op_sel_hi:[1,1,0]
	v_and_b32_e32 v81, 0x7fffffff, v75
	v_pk_fma_f32 v[86:87], v[82:83], v[86:87], s[40:41] op_sel_hi:[1,1,0]
	v_and_b32_e32 v80, 0x7fffffff, v74
	v_pk_fma_f32 v[86:87], v[82:83], v[86:87], s[74:75] op_sel_hi:[1,1,0]
	v_max_f32_e32 v72, 0, v72
	v_pk_fma_f32 v[86:87], v[82:83], v[86:87], s[76:77] op_sel_hi:[1,1,0]
	v_max_f32_e32 v73, 0, v73
	v_pk_mul_f32 v[86:87], v[86:87], v[86:87]
	v_max_f32_e32 v74, v74, v74
	v_pk_mul_f32 v[86:87], v[86:87], v[86:87]
	v_max_f32_e32 v75, v75, v75
	v_pk_mul_f32 v[86:87], v[86:87], v[86:87]
	v_max_f32_e32 v74, 0, v74
	v_pk_mul_f32 v[86:87], v[86:87], v[86:87]
	v_max_f32_e32 v75, 0, v75
	v_rcp_f32_e32 v86, v86
	v_rcp_f32_e32 v87, v87
	s_nop 0
	v_pk_fma_f32 v[82:83], v[82:83], v[86:87], v[72:73] neg_lo:[1,0,0] neg_hi:[1,0,0]
	v_pk_fma_f32 v[72:73], v[80:81], s[94:95], v[152:153] op_sel_hi:[1,0,0]
	v_pk_fma_f32 v[86:87], v[76:77], v[76:77], v[88:89]
	v_pk_fma_f32 v[72:73], v[80:81], v[72:73], s[96:97] op_sel_hi:[1,1,0]
	v_pk_fma_f32 v[88:89], v[82:83], v[82:83], v[90:91]
	v_pk_fma_f32 v[72:73], v[80:81], v[72:73], s[98:99] op_sel_hi:[1,1,0]
	v_pk_fma_f32 v[90:91], v[78:79], v[78:79], v[92:93]
	v_pk_fma_f32 v[72:73], v[80:81], v[72:73], s[40:41] op_sel_hi:[1,1,0]
	s_nop 0
	v_pk_fma_f32 v[72:73], v[80:81], v[72:73], s[74:75] op_sel_hi:[1,1,0]
	s_nop 0
	v_pk_fma_f32 v[72:73], v[80:81], v[72:73], s[76:77] op_sel_hi:[1,1,0]
	s_nop 0
	v_pk_mul_f32 v[72:73], v[72:73], v[72:73]
	s_nop 0
	v_pk_mul_f32 v[72:73], v[72:73], v[72:73]
	s_nop 0
	v_pk_mul_f32 v[72:73], v[72:73], v[72:73]
	s_nop 0
	v_pk_mul_f32 v[72:73], v[72:73], v[72:73]
	s_nop 0
	v_rcp_f32_e32 v72, v72
	v_rcp_f32_e32 v73, v73
	s_nop 0
	v_pk_fma_f32 v[80:81], v[80:81], v[72:73], v[74:75] neg_lo:[1,0,0] neg_hi:[1,0,0]
	v_cvt_pk_bf16_f32 v72, v76, v77
	v_cvt_pk_bf16_f32 v73, v78, v79
	v_cvt_pk_bf16_f32 v74, v82, v83
	s_nop 0
	v_cvt_pk_bf16_f32 v75, v80, v81
	global_store_dwordx4 v[102:103], v[72:75], off offset:128 sc1
	v_pk_fma_f32 v[92:93], v[80:81], v[80:81], v[94:95]
	s_nop 0
	v_and_b32_e32 v75, 0x7fffffff, v69
	v_and_b32_e32 v74, 0x7fffffff, v68
	v_pk_fma_f32 v[76:77], v[74:75], s[94:95], v[152:153] op_sel_hi:[1,0,0]
	v_max_f32_e32 v68, v68, v68
	v_pk_fma_f32 v[76:77], v[74:75], v[76:77], s[96:97] op_sel_hi:[1,1,0]
	v_max_f32_e32 v69, v69, v69
	v_pk_fma_f32 v[76:77], v[74:75], v[76:77], s[98:99] op_sel_hi:[1,1,0]
	v_and_b32_e32 v73, 0x7fffffff, v71
	v_pk_fma_f32 v[76:77], v[74:75], v[76:77], s[40:41] op_sel_hi:[1,1,0]
	v_and_b32_e32 v72, 0x7fffffff, v70
	v_pk_fma_f32 v[76:77], v[74:75], v[76:77], s[74:75] op_sel_hi:[1,1,0]
	v_max_f32_e32 v68, 0, v68
	v_pk_fma_f32 v[76:77], v[74:75], v[76:77], s[76:77] op_sel_hi:[1,1,0]
	v_max_f32_e32 v69, 0, v69
	v_pk_mul_f32 v[76:77], v[76:77], v[76:77]
	v_max_f32_e32 v70, v70, v70
	v_pk_mul_f32 v[76:77], v[76:77], v[76:77]
	v_max_f32_e32 v71, v71, v71
	v_pk_mul_f32 v[76:77], v[76:77], v[76:77]
	v_max_f32_e32 v70, 0, v70
	v_pk_mul_f32 v[76:77], v[76:77], v[76:77]
	v_max_f32_e32 v71, 0, v71
	v_rcp_f32_e32 v76, v76
	v_rcp_f32_e32 v77, v77
	s_nop 0
	v_pk_fma_f32 v[74:75], v[74:75], v[76:77], v[68:69] neg_lo:[1,0,0] neg_hi:[1,0,0]
	v_pk_fma_f32 v[68:69], v[72:73], s[94:95], v[152:153] op_sel_hi:[1,0,0]
	s_nop 0
	v_pk_fma_f32 v[68:69], v[72:73], v[68:69], s[96:97] op_sel_hi:[1,1,0]
	s_nop 0
	v_pk_fma_f32 v[68:69], v[72:73], v[68:69], s[98:99] op_sel_hi:[1,1,0]
	s_nop 0
	v_pk_fma_f32 v[68:69], v[72:73], v[68:69], s[40:41] op_sel_hi:[1,1,0]
	s_nop 0
	v_pk_fma_f32 v[68:69], v[72:73], v[68:69], s[74:75] op_sel_hi:[1,1,0]
	s_nop 0
	v_pk_fma_f32 v[68:69], v[72:73], v[68:69], s[76:77] op_sel_hi:[1,1,0]
	s_nop 0
	v_pk_mul_f32 v[68:69], v[68:69], v[68:69]
	s_nop 0
	v_pk_mul_f32 v[68:69], v[68:69], v[68:69]
	s_nop 0
	v_pk_mul_f32 v[68:69], v[68:69], v[68:69]
	s_nop 0
	v_pk_mul_f32 v[68:69], v[68:69], v[68:69]
	s_nop 0
	v_rcp_f32_e32 v68, v68
	v_rcp_f32_e32 v69, v69
	s_nop 0
	v_pk_fma_f32 v[76:77], v[72:73], v[68:69], v[70:71] neg_lo:[1,0,0] neg_hi:[1,0,0]
	v_and_b32_e32 v71, 0x7fffffff, v65
	v_and_b32_e32 v70, 0x7fffffff, v64
	v_pk_fma_f32 v[72:73], v[70:71], s[94:95], v[152:153] op_sel_hi:[1,0,0]
	v_max_f32_e32 v64, v64, v64
	v_pk_fma_f32 v[72:73], v[70:71], v[72:73], s[96:97] op_sel_hi:[1,1,0]
	v_max_f32_e32 v65, v65, v65
	v_pk_fma_f32 v[72:73], v[70:71], v[72:73], s[98:99] op_sel_hi:[1,1,0]
	v_and_b32_e32 v69, 0x7fffffff, v67
	v_pk_fma_f32 v[72:73], v[70:71], v[72:73], s[40:41] op_sel_hi:[1,1,0]
	v_and_b32_e32 v68, 0x7fffffff, v66
	v_pk_fma_f32 v[72:73], v[70:71], v[72:73], s[74:75] op_sel_hi:[1,1,0]
	v_max_f32_e32 v64, 0, v64
	v_pk_fma_f32 v[72:73], v[70:71], v[72:73], s[76:77] op_sel_hi:[1,1,0]
	v_max_f32_e32 v65, 0, v65
	v_pk_mul_f32 v[72:73], v[72:73], v[72:73]
	v_max_f32_e32 v66, v66, v66
	v_pk_mul_f32 v[72:73], v[72:73], v[72:73]
	v_max_f32_e32 v67, v67, v67
	v_pk_mul_f32 v[72:73], v[72:73], v[72:73]
	v_max_f32_e32 v66, 0, v66
	v_pk_mul_f32 v[72:73], v[72:73], v[72:73]
	v_max_f32_e32 v67, 0, v67
	v_rcp_f32_e32 v72, v72
	v_rcp_f32_e32 v73, v73
	s_nop 0
	v_pk_fma_f32 v[78:79], v[70:71], v[72:73], v[64:65] neg_lo:[1,0,0] neg_hi:[1,0,0]
	v_pk_fma_f32 v[64:65], v[68:69], s[94:95], v[152:153] op_sel_hi:[1,0,0]
	v_cvt_pk_bf16_f32 v72, v74, v75
	v_cvt_pk_bf16_f32 v73, v76, v77
	s_nop 0
	v_pk_fma_f32 v[64:65], v[68:69], v[64:65], s[96:97] op_sel_hi:[1,1,0]
	s_nop 0
	v_pk_fma_f32 v[64:65], v[68:69], v[64:65], s[98:99] op_sel_hi:[1,1,0]
	s_nop 0
	v_pk_fma_f32 v[64:65], v[68:69], v[64:65], s[40:41] op_sel_hi:[1,1,0]
	s_nop 0
	v_pk_fma_f32 v[64:65], v[68:69], v[64:65], s[74:75] op_sel_hi:[1,1,0]
	s_nop 0
	v_pk_fma_f32 v[64:65], v[68:69], v[64:65], s[76:77] op_sel_hi:[1,1,0]
	s_nop 0
	v_pk_mul_f32 v[64:65], v[64:65], v[64:65]
	s_nop 0
	v_pk_mul_f32 v[64:65], v[64:65], v[64:65]
	s_nop 0
	v_pk_mul_f32 v[64:65], v[64:65], v[64:65]
	s_nop 0
	v_pk_mul_f32 v[64:65], v[64:65], v[64:65]
	s_nop 0
	v_rcp_f32_e32 v64, v64
	v_rcp_f32_e32 v65, v65
	s_nop 0
	v_pk_fma_f32 v[80:81], v[68:69], v[64:65], v[66:67] neg_lo:[1,0,0] neg_hi:[1,0,0]
	v_pk_fma_f32 v[64:65], v[74:75], v[74:75], v[96:97]
	v_cvt_pk_bf16_f32 v74, v78, v79
	v_cvt_pk_bf16_f32 v75, v80, v81
	global_store_dwordx4 v[84:85], v[72:75], off offset:128 sc1
	v_pk_fma_f32 v[68:69], v[76:77], v[76:77], v[106:107]
	v_pk_fma_f32 v[66:67], v[78:79], v[78:79], v[104:105]
	v_and_b32_e32 v75, 0x7fffffff, v61
	v_and_b32_e32 v74, 0x7fffffff, v60
	v_pk_fma_f32 v[76:77], v[74:75], s[94:95], v[152:153] op_sel_hi:[1,0,0]
	v_max_f32_e32 v60, v60, v60
	v_pk_fma_f32 v[76:77], v[74:75], v[76:77], s[96:97] op_sel_hi:[1,1,0]
	v_max_f32_e32 v61, v61, v61
	v_pk_fma_f32 v[76:77], v[74:75], v[76:77], s[98:99] op_sel_hi:[1,1,0]
	v_and_b32_e32 v73, 0x7fffffff, v63
	v_pk_fma_f32 v[76:77], v[74:75], v[76:77], s[40:41] op_sel_hi:[1,1,0]
	v_and_b32_e32 v72, 0x7fffffff, v62
	v_pk_fma_f32 v[76:77], v[74:75], v[76:77], s[74:75] op_sel_hi:[1,1,0]
	v_max_f32_e32 v60, 0, v60
	v_pk_fma_f32 v[76:77], v[74:75], v[76:77], s[76:77] op_sel_hi:[1,1,0]
	v_max_f32_e32 v61, 0, v61
	v_pk_mul_f32 v[76:77], v[76:77], v[76:77]
	v_max_f32_e32 v62, v62, v62
	v_pk_mul_f32 v[76:77], v[76:77], v[76:77]
	v_max_f32_e32 v63, v63, v63
	v_pk_mul_f32 v[76:77], v[76:77], v[76:77]
	v_max_f32_e32 v62, 0, v62
	v_pk_mul_f32 v[76:77], v[76:77], v[76:77]
	v_max_f32_e32 v63, 0, v63
	v_rcp_f32_e32 v76, v76
	v_rcp_f32_e32 v77, v77
	v_pk_fma_f32 v[70:71], v[80:81], v[80:81], v[108:109]
	v_pk_fma_f32 v[74:75], v[74:75], v[76:77], v[60:61] neg_lo:[1,0,0] neg_hi:[1,0,0]
	v_pk_fma_f32 v[60:61], v[72:73], s[94:95], v[152:153] op_sel_hi:[1,0,0]
	s_nop 0
	v_pk_fma_f32 v[60:61], v[72:73], v[60:61], s[96:97] op_sel_hi:[1,1,0]
	s_nop 0
	v_pk_fma_f32 v[60:61], v[72:73], v[60:61], s[98:99] op_sel_hi:[1,1,0]
	s_nop 0
	v_pk_fma_f32 v[60:61], v[72:73], v[60:61], s[40:41] op_sel_hi:[1,1,0]
	s_nop 0
	v_pk_fma_f32 v[60:61], v[72:73], v[60:61], s[74:75] op_sel_hi:[1,1,0]
	s_nop 0
	v_pk_fma_f32 v[60:61], v[72:73], v[60:61], s[76:77] op_sel_hi:[1,1,0]
	s_nop 0
	v_pk_mul_f32 v[60:61], v[60:61], v[60:61]
	s_nop 0
	v_pk_mul_f32 v[60:61], v[60:61], v[60:61]
	s_nop 0
	v_pk_mul_f32 v[60:61], v[60:61], v[60:61]
	s_nop 0
	v_pk_mul_f32 v[60:61], v[60:61], v[60:61]
	s_nop 0
	v_rcp_f32_e32 v60, v60
	v_rcp_f32_e32 v61, v61
	s_nop 0
	v_pk_fma_f32 v[76:77], v[72:73], v[60:61], v[62:63] neg_lo:[1,0,0] neg_hi:[1,0,0]
	v_and_b32_e32 v63, 0x7fffffff, v57
	v_and_b32_e32 v62, 0x7fffffff, v56
	v_pk_fma_f32 v[72:73], v[62:63], s[94:95], v[152:153] op_sel_hi:[1,0,0]
	v_max_f32_e32 v56, v56, v56
	v_pk_fma_f32 v[72:73], v[62:63], v[72:73], s[96:97] op_sel_hi:[1,1,0]
	v_max_f32_e32 v57, v57, v57
	v_pk_fma_f32 v[72:73], v[62:63], v[72:73], s[98:99] op_sel_hi:[1,1,0]
	v_and_b32_e32 v61, 0x7fffffff, v59
	v_pk_fma_f32 v[72:73], v[62:63], v[72:73], s[40:41] op_sel_hi:[1,1,0]
	v_and_b32_e32 v60, 0x7fffffff, v58
	v_pk_fma_f32 v[72:73], v[62:63], v[72:73], s[74:75] op_sel_hi:[1,1,0]
	v_max_f32_e32 v56, 0, v56
	v_pk_fma_f32 v[72:73], v[62:63], v[72:73], s[76:77] op_sel_hi:[1,1,0]
	v_max_f32_e32 v57, 0, v57
	v_pk_mul_f32 v[72:73], v[72:73], v[72:73]
	v_max_f32_e32 v58, v58, v58
	v_pk_mul_f32 v[72:73], v[72:73], v[72:73]
	v_max_f32_e32 v59, v59, v59
	v_pk_mul_f32 v[72:73], v[72:73], v[72:73]
	v_max_f32_e32 v58, 0, v58
	v_pk_mul_f32 v[72:73], v[72:73], v[72:73]
	v_max_f32_e32 v59, 0, v59
	v_rcp_f32_e32 v72, v72
	v_rcp_f32_e32 v73, v73
	s_nop 0
	v_pk_fma_f32 v[78:79], v[62:63], v[72:73], v[56:57] neg_lo:[1,0,0] neg_hi:[1,0,0]
	v_pk_fma_f32 v[56:57], v[60:61], s[94:95], v[152:153] op_sel_hi:[1,0,0]
	v_cvt_pk_bf16_f32 v72, v74, v75
	v_cvt_pk_bf16_f32 v73, v76, v77
	s_nop 0
	v_pk_fma_f32 v[56:57], v[60:61], v[56:57], s[96:97] op_sel_hi:[1,1,0]
	s_nop 0
	v_pk_fma_f32 v[56:57], v[60:61], v[56:57], s[98:99] op_sel_hi:[1,1,0]
	s_nop 0
	v_pk_fma_f32 v[56:57], v[60:61], v[56:57], s[40:41] op_sel_hi:[1,1,0]
	s_nop 0
	v_pk_fma_f32 v[56:57], v[60:61], v[56:57], s[74:75] op_sel_hi:[1,1,0]
	s_nop 0
	v_pk_fma_f32 v[56:57], v[60:61], v[56:57], s[76:77] op_sel_hi:[1,1,0]
	s_nop 0
	v_pk_mul_f32 v[56:57], v[56:57], v[56:57]
	s_nop 0
	v_pk_mul_f32 v[56:57], v[56:57], v[56:57]
	s_nop 0
	v_pk_mul_f32 v[56:57], v[56:57], v[56:57]
	s_nop 0
	v_pk_mul_f32 v[56:57], v[56:57], v[56:57]
	s_nop 0
	v_rcp_f32_e32 v56, v56
	v_rcp_f32_e32 v57, v57
	s_nop 0
	v_pk_fma_f32 v[80:81], v[60:61], v[56:57], v[58:59] neg_lo:[1,0,0] neg_hi:[1,0,0]
	v_pk_fma_f32 v[60:61], v[76:77], v[76:77], v[90:91]
	v_mov_b32_e32 v77, s12
	v_or_b32_e32 v76, s11, v138
	v_lshlrev_b64 v[76:77], 10, v[76:77]
	v_pk_fma_f32 v[56:57], v[74:75], v[74:75], v[86:87]
	v_cvt_pk_bf16_f32 v74, v78, v79
	v_cvt_pk_bf16_f32 v75, v80, v81
	v_lshl_add_u64 v[76:77], v[142:143], 0, v[76:77]
	global_store_dwordx4 v[76:77], v[72:75], off sc1
	v_pk_fma_f32 v[58:59], v[78:79], v[78:79], v[88:89]
	v_pk_fma_f32 v[62:63], v[80:81], v[80:81], v[92:93]
	v_and_b32_e32 v75, 0x7fffffff, v53
	v_and_b32_e32 v74, 0x7fffffff, v52
	v_pk_fma_f32 v[78:79], v[74:75], s[94:95], v[152:153] op_sel_hi:[1,0,0]
	v_max_f32_e32 v52, v52, v52
	v_pk_fma_f32 v[78:79], v[74:75], v[78:79], s[96:97] op_sel_hi:[1,1,0]
	v_max_f32_e32 v53, v53, v53
	v_pk_fma_f32 v[78:79], v[74:75], v[78:79], s[98:99] op_sel_hi:[1,1,0]
	v_and_b32_e32 v73, 0x7fffffff, v55
	v_pk_fma_f32 v[78:79], v[74:75], v[78:79], s[40:41] op_sel_hi:[1,1,0]
	v_and_b32_e32 v72, 0x7fffffff, v54
	v_pk_fma_f32 v[78:79], v[74:75], v[78:79], s[74:75] op_sel_hi:[1,1,0]
	v_max_f32_e32 v52, 0, v52
	v_pk_fma_f32 v[78:79], v[74:75], v[78:79], s[76:77] op_sel_hi:[1,1,0]
	v_max_f32_e32 v53, 0, v53
	v_pk_mul_f32 v[78:79], v[78:79], v[78:79]
	v_max_f32_e32 v54, v54, v54
	v_pk_mul_f32 v[78:79], v[78:79], v[78:79]
	v_max_f32_e32 v55, v55, v55
	v_pk_mul_f32 v[78:79], v[78:79], v[78:79]
	v_max_f32_e32 v54, 0, v54
	v_pk_mul_f32 v[78:79], v[78:79], v[78:79]
	v_max_f32_e32 v55, 0, v55
	v_rcp_f32_e32 v78, v78
	v_rcp_f32_e32 v79, v79
	s_nop 0
	v_pk_fma_f32 v[52:53], v[74:75], v[78:79], v[52:53] neg_lo:[1,0,0] neg_hi:[1,0,0]
	v_pk_fma_f32 v[74:75], v[72:73], s[94:95], v[152:153] op_sel_hi:[1,0,0]
	v_pk_fma_f32 v[64:65], v[52:53], v[52:53], v[64:65]
	v_pk_fma_f32 v[74:75], v[72:73], v[74:75], s[96:97] op_sel_hi:[1,1,0]
	s_nop 0
	v_pk_fma_f32 v[74:75], v[72:73], v[74:75], s[98:99] op_sel_hi:[1,1,0]
	s_nop 0
	v_pk_fma_f32 v[74:75], v[72:73], v[74:75], s[40:41] op_sel_hi:[1,1,0]
	s_nop 0
	v_pk_fma_f32 v[74:75], v[72:73], v[74:75], s[74:75] op_sel_hi:[1,1,0]
	s_nop 0
	v_pk_fma_f32 v[74:75], v[72:73], v[74:75], s[76:77] op_sel_hi:[1,1,0]
	s_nop 0
	v_pk_mul_f32 v[74:75], v[74:75], v[74:75]
	s_nop 0
	v_pk_mul_f32 v[74:75], v[74:75], v[74:75]
	s_nop 0
	v_pk_mul_f32 v[74:75], v[74:75], v[74:75]
	s_nop 0
	v_pk_mul_f32 v[74:75], v[74:75], v[74:75]
	s_nop 0
	v_rcp_f32_e32 v74, v74
	v_rcp_f32_e32 v75, v75
	s_nop 0
	v_pk_fma_f32 v[54:55], v[72:73], v[74:75], v[54:55] neg_lo:[1,0,0] neg_hi:[1,0,0]
	v_and_b32_e32 v75, 0x7fffffff, v49
	v_and_b32_e32 v74, 0x7fffffff, v48
	v_pk_fma_f32 v[78:79], v[74:75], s[94:95], v[152:153] op_sel_hi:[1,0,0]
	v_max_f32_e32 v48, v48, v48
	v_pk_fma_f32 v[78:79], v[74:75], v[78:79], s[96:97] op_sel_hi:[1,1,0]
	v_max_f32_e32 v49, v49, v49
	v_pk_fma_f32 v[78:79], v[74:75], v[78:79], s[98:99] op_sel_hi:[1,1,0]
	v_and_b32_e32 v73, 0x7fffffff, v51
	v_pk_fma_f32 v[78:79], v[74:75], v[78:79], s[40:41] op_sel_hi:[1,1,0]
	v_and_b32_e32 v72, 0x7fffffff, v50
	v_pk_fma_f32 v[78:79], v[74:75], v[78:79], s[74:75] op_sel_hi:[1,1,0]
	v_max_f32_e32 v48, 0, v48
	v_pk_fma_f32 v[78:79], v[74:75], v[78:79], s[76:77] op_sel_hi:[1,1,0]
	v_max_f32_e32 v49, 0, v49
	v_pk_mul_f32 v[78:79], v[78:79], v[78:79]
	v_max_f32_e32 v50, v50, v50
	v_pk_mul_f32 v[78:79], v[78:79], v[78:79]
	v_max_f32_e32 v51, v51, v51
	v_pk_mul_f32 v[78:79], v[78:79], v[78:79]
	v_max_f32_e32 v50, 0, v50
	v_pk_mul_f32 v[78:79], v[78:79], v[78:79]
	v_max_f32_e32 v51, 0, v51
	v_rcp_f32_e32 v78, v78
	v_rcp_f32_e32 v79, v79
	v_pk_fma_f32 v[68:69], v[54:55], v[54:55], v[68:69]
	v_pk_fma_f32 v[74:75], v[74:75], v[78:79], v[48:49] neg_lo:[1,0,0] neg_hi:[1,0,0]
	v_pk_fma_f32 v[48:49], v[72:73], s[94:95], v[152:153] op_sel_hi:[1,0,0]
	v_pk_fma_f32 v[66:67], v[74:75], v[74:75], v[66:67]
	v_pk_fma_f32 v[48:49], v[72:73], v[48:49], s[96:97] op_sel_hi:[1,1,0]
	s_nop 0
	v_pk_fma_f32 v[48:49], v[72:73], v[48:49], s[98:99] op_sel_hi:[1,1,0]
	s_nop 0
	v_pk_fma_f32 v[48:49], v[72:73], v[48:49], s[40:41] op_sel_hi:[1,1,0]
	s_nop 0
	v_pk_fma_f32 v[48:49], v[72:73], v[48:49], s[74:75] op_sel_hi:[1,1,0]
	s_nop 0
	v_pk_fma_f32 v[48:49], v[72:73], v[48:49], s[76:77] op_sel_hi:[1,1,0]
	s_nop 0
	v_pk_mul_f32 v[48:49], v[48:49], v[48:49]
	s_nop 0
	v_pk_mul_f32 v[48:49], v[48:49], v[48:49]
	s_nop 0
	v_pk_mul_f32 v[48:49], v[48:49], v[48:49]
	s_nop 0
	v_pk_mul_f32 v[48:49], v[48:49], v[48:49]
	s_nop 0
	v_rcp_f32_e32 v48, v48
	v_rcp_f32_e32 v49, v49
	s_nop 0
	v_pk_fma_f32 v[72:73], v[72:73], v[48:49], v[50:51] neg_lo:[1,0,0] neg_hi:[1,0,0]
	v_cvt_pk_bf16_f32 v48, v52, v53
	v_mov_b32_e32 v53, s5
	v_or_b32_e32 v52, s4, v138
	v_lshlrev_b64 v[52:53], 10, v[52:53]
	v_cvt_pk_bf16_f32 v49, v54, v55
	v_cvt_pk_bf16_f32 v50, v74, v75
	v_cvt_pk_bf16_f32 v51, v72, v73
	v_lshl_add_u64 v[52:53], v[142:143], 0, v[52:53]
	global_store_dwordx4 v[52:53], v[48:51], off sc1
	s_add_u32 s4, s0, vcc_lo
	v_pk_fma_f32 v[70:71], v[72:73], v[72:73], v[70:71]
	v_and_b32_e32 v51, 0x7fffffff, v45
	v_and_b32_e32 v50, 0x7fffffff, v44
	v_pk_fma_f32 v[54:55], v[50:51], s[94:95], v[152:153] op_sel_hi:[1,0,0]
	v_max_f32_e32 v44, v44, v44
	v_pk_fma_f32 v[54:55], v[50:51], v[54:55], s[96:97] op_sel_hi:[1,1,0]
	v_max_f32_e32 v45, v45, v45
	v_pk_fma_f32 v[54:55], v[50:51], v[54:55], s[98:99] op_sel_hi:[1,1,0]
	v_and_b32_e32 v49, 0x7fffffff, v47
	v_pk_fma_f32 v[54:55], v[50:51], v[54:55], s[40:41] op_sel_hi:[1,1,0]
	v_and_b32_e32 v48, 0x7fffffff, v46
	v_pk_fma_f32 v[54:55], v[50:51], v[54:55], s[74:75] op_sel_hi:[1,1,0]
	v_max_f32_e32 v44, 0, v44
	v_pk_fma_f32 v[54:55], v[50:51], v[54:55], s[76:77] op_sel_hi:[1,1,0]
	v_max_f32_e32 v45, 0, v45
	v_pk_mul_f32 v[54:55], v[54:55], v[54:55]
	v_max_f32_e32 v46, v46, v46
	v_pk_mul_f32 v[54:55], v[54:55], v[54:55]
	v_max_f32_e32 v47, v47, v47
	v_pk_mul_f32 v[54:55], v[54:55], v[54:55]
	v_max_f32_e32 v46, 0, v46
	v_pk_mul_f32 v[54:55], v[54:55], v[54:55]
	v_max_f32_e32 v47, 0, v47
	v_rcp_f32_e32 v54, v54
	v_rcp_f32_e32 v55, v55
	s_addc_u32 s5, s1, vcc_hi
	s_add_u32 s0, s82, s0
	s_addc_u32 s1, s83, s1
	v_pk_fma_f32 v[44:45], v[50:51], v[54:55], v[44:45] neg_lo:[1,0,0] neg_hi:[1,0,0]
	v_pk_fma_f32 v[50:51], v[48:49], s[94:95], v[152:153] op_sel_hi:[1,0,0]
	s_andn2_b64 vcc, exec, s[88:89]
	v_pk_fma_f32 v[50:51], v[48:49], v[50:51], s[96:97] op_sel_hi:[1,1,0]
	s_nop 0
	v_pk_fma_f32 v[50:51], v[48:49], v[50:51], s[98:99] op_sel_hi:[1,1,0]
	s_nop 0
	v_pk_fma_f32 v[50:51], v[48:49], v[50:51], s[40:41] op_sel_hi:[1,1,0]
	s_nop 0
	v_pk_fma_f32 v[50:51], v[48:49], v[50:51], s[74:75] op_sel_hi:[1,1,0]
	s_nop 0
	v_pk_fma_f32 v[50:51], v[48:49], v[50:51], s[76:77] op_sel_hi:[1,1,0]
	s_nop 0
	v_pk_mul_f32 v[50:51], v[50:51], v[50:51]
	s_nop 0
	v_pk_mul_f32 v[50:51], v[50:51], v[50:51]
	s_nop 0
	v_pk_mul_f32 v[50:51], v[50:51], v[50:51]
	s_nop 0
	v_pk_mul_f32 v[50:51], v[50:51], v[50:51]
	s_nop 0
	v_rcp_f32_e32 v50, v50
	v_rcp_f32_e32 v51, v51
	s_nop 0
	v_pk_fma_f32 v[46:47], v[48:49], v[50:51], v[46:47] neg_lo:[1,0,0] neg_hi:[1,0,0]
	v_and_b32_e32 v51, 0x7fffffff, v41
	v_and_b32_e32 v50, 0x7fffffff, v40
	v_pk_fma_f32 v[54:55], v[50:51], s[94:95], v[152:153] op_sel_hi:[1,0,0]
	v_max_f32_e32 v40, v40, v40
	v_pk_fma_f32 v[54:55], v[50:51], v[54:55], s[96:97] op_sel_hi:[1,1,0]
	v_max_f32_e32 v41, v41, v41
	v_pk_fma_f32 v[54:55], v[50:51], v[54:55], s[98:99] op_sel_hi:[1,1,0]
	v_and_b32_e32 v49, 0x7fffffff, v43
	v_pk_fma_f32 v[54:55], v[50:51], v[54:55], s[40:41] op_sel_hi:[1,1,0]
	v_and_b32_e32 v48, 0x7fffffff, v42
	v_pk_fma_f32 v[54:55], v[50:51], v[54:55], s[74:75] op_sel_hi:[1,1,0]
	v_max_f32_e32 v40, 0, v40
	v_pk_fma_f32 v[54:55], v[50:51], v[54:55], s[76:77] op_sel_hi:[1,1,0]
	v_max_f32_e32 v41, 0, v41
	v_pk_mul_f32 v[54:55], v[54:55], v[54:55]
	v_max_f32_e32 v42, v42, v42
	v_pk_mul_f32 v[54:55], v[54:55], v[54:55]
	v_max_f32_e32 v43, v43, v43
	v_pk_mul_f32 v[54:55], v[54:55], v[54:55]
	v_max_f32_e32 v42, 0, v42
	v_pk_mul_f32 v[54:55], v[54:55], v[54:55]
	v_max_f32_e32 v43, 0, v43
	v_rcp_f32_e32 v54, v54
	v_rcp_f32_e32 v55, v55
	s_nop 0
	v_pk_fma_f32 v[50:51], v[50:51], v[54:55], v[40:41] neg_lo:[1,0,0] neg_hi:[1,0,0]
	v_pk_fma_f32 v[40:41], v[48:49], s[94:95], v[152:153] op_sel_hi:[1,0,0]
	v_pk_fma_f32 v[54:55], v[44:45], v[44:45], v[56:57]
	v_pk_fma_f32 v[40:41], v[48:49], v[40:41], s[96:97] op_sel_hi:[1,1,0]
	v_pk_fma_f32 v[56:57], v[50:51], v[50:51], v[58:59]
	v_pk_fma_f32 v[40:41], v[48:49], v[40:41], s[98:99] op_sel_hi:[1,1,0]
	v_pk_fma_f32 v[58:59], v[46:47], v[46:47], v[60:61]
	v_pk_fma_f32 v[40:41], v[48:49], v[40:41], s[40:41] op_sel_hi:[1,1,0]
	s_nop 0
	v_pk_fma_f32 v[40:41], v[48:49], v[40:41], s[74:75] op_sel_hi:[1,1,0]
	s_nop 0
	v_pk_fma_f32 v[40:41], v[48:49], v[40:41], s[76:77] op_sel_hi:[1,1,0]
	s_nop 0
	v_pk_mul_f32 v[40:41], v[40:41], v[40:41]
	s_nop 0
	v_pk_mul_f32 v[40:41], v[40:41], v[40:41]
	s_nop 0
	v_pk_mul_f32 v[40:41], v[40:41], v[40:41]
	s_nop 0
	v_pk_mul_f32 v[40:41], v[40:41], v[40:41]
	s_nop 0
	v_rcp_f32_e32 v40, v40
	v_rcp_f32_e32 v41, v41
	s_nop 0
	v_pk_fma_f32 v[48:49], v[48:49], v[40:41], v[42:43] neg_lo:[1,0,0] neg_hi:[1,0,0]
	v_cvt_pk_bf16_f32 v40, v44, v45
	v_cvt_pk_bf16_f32 v41, v46, v47
	v_cvt_pk_bf16_f32 v42, v50, v51
	s_nop 0
	v_cvt_pk_bf16_f32 v43, v48, v49
	global_store_dwordx4 v[76:77], v[40:43], off offset:128 sc1
	v_pk_fma_f32 v[60:61], v[48:49], v[48:49], v[62:63]
	s_nop 0
	v_and_b32_e32 v43, 0x7fffffff, v37
	v_and_b32_e32 v42, 0x7fffffff, v36
	v_pk_fma_f32 v[44:45], v[42:43], s[94:95], v[152:153] op_sel_hi:[1,0,0]
	v_max_f32_e32 v36, v36, v36
	v_pk_fma_f32 v[44:45], v[42:43], v[44:45], s[96:97] op_sel_hi:[1,1,0]
	v_max_f32_e32 v37, v37, v37
	v_pk_fma_f32 v[44:45], v[42:43], v[44:45], s[98:99] op_sel_hi:[1,1,0]
	v_and_b32_e32 v41, 0x7fffffff, v39
	v_pk_fma_f32 v[44:45], v[42:43], v[44:45], s[40:41] op_sel_hi:[1,1,0]
	v_and_b32_e32 v40, 0x7fffffff, v38
	v_pk_fma_f32 v[44:45], v[42:43], v[44:45], s[74:75] op_sel_hi:[1,1,0]
	v_max_f32_e32 v36, 0, v36
	v_pk_fma_f32 v[44:45], v[42:43], v[44:45], s[76:77] op_sel_hi:[1,1,0]
	v_max_f32_e32 v37, 0, v37
	v_pk_mul_f32 v[44:45], v[44:45], v[44:45]
	v_max_f32_e32 v38, v38, v38
	v_pk_mul_f32 v[44:45], v[44:45], v[44:45]
	v_max_f32_e32 v39, v39, v39
	v_pk_mul_f32 v[44:45], v[44:45], v[44:45]
	v_max_f32_e32 v38, 0, v38
	v_pk_mul_f32 v[44:45], v[44:45], v[44:45]
	v_max_f32_e32 v39, 0, v39
	v_rcp_f32_e32 v44, v44
	v_rcp_f32_e32 v45, v45
	s_nop 0
	v_pk_fma_f32 v[36:37], v[42:43], v[44:45], v[36:37] neg_lo:[1,0,0] neg_hi:[1,0,0]
	v_pk_fma_f32 v[42:43], v[40:41], s[94:95], v[152:153] op_sel_hi:[1,0,0]
	s_nop 0
	v_pk_fma_f32 v[42:43], v[40:41], v[42:43], s[96:97] op_sel_hi:[1,1,0]
	s_nop 0
	v_pk_fma_f32 v[42:43], v[40:41], v[42:43], s[98:99] op_sel_hi:[1,1,0]
	s_nop 0
	v_pk_fma_f32 v[42:43], v[40:41], v[42:43], s[40:41] op_sel_hi:[1,1,0]
	s_nop 0
	v_pk_fma_f32 v[42:43], v[40:41], v[42:43], s[74:75] op_sel_hi:[1,1,0]
	s_nop 0
	v_pk_fma_f32 v[42:43], v[40:41], v[42:43], s[76:77] op_sel_hi:[1,1,0]
	s_nop 0
	v_pk_mul_f32 v[42:43], v[42:43], v[42:43]
	s_nop 0
	v_pk_mul_f32 v[42:43], v[42:43], v[42:43]
	s_nop 0
	v_pk_mul_f32 v[42:43], v[42:43], v[42:43]
	s_nop 0
	v_pk_mul_f32 v[42:43], v[42:43], v[42:43]
	s_nop 0
	v_rcp_f32_e32 v42, v42
	v_rcp_f32_e32 v43, v43
	s_nop 0
	v_pk_fma_f32 v[38:39], v[40:41], v[42:43], v[38:39] neg_lo:[1,0,0] neg_hi:[1,0,0]
	v_and_b32_e32 v43, 0x7fffffff, v33
	v_and_b32_e32 v42, 0x7fffffff, v32
	v_pk_fma_f32 v[44:45], v[42:43], s[94:95], v[152:153] op_sel_hi:[1,0,0]
	v_max_f32_e32 v32, v32, v32
	v_pk_fma_f32 v[44:45], v[42:43], v[44:45], s[96:97] op_sel_hi:[1,1,0]
	v_max_f32_e32 v33, v33, v33
	v_pk_fma_f32 v[44:45], v[42:43], v[44:45], s[98:99] op_sel_hi:[1,1,0]
	v_and_b32_e32 v41, 0x7fffffff, v35
	v_pk_fma_f32 v[44:45], v[42:43], v[44:45], s[40:41] op_sel_hi:[1,1,0]
	v_and_b32_e32 v40, 0x7fffffff, v34
	v_pk_fma_f32 v[44:45], v[42:43], v[44:45], s[74:75] op_sel_hi:[1,1,0]
	v_max_f32_e32 v32, 0, v32
	v_pk_fma_f32 v[44:45], v[42:43], v[44:45], s[76:77] op_sel_hi:[1,1,0]
	v_max_f32_e32 v33, 0, v33
	v_pk_mul_f32 v[44:45], v[44:45], v[44:45]
	v_max_f32_e32 v34, v34, v34
	v_pk_mul_f32 v[44:45], v[44:45], v[44:45]
	v_max_f32_e32 v35, v35, v35
	v_pk_mul_f32 v[44:45], v[44:45], v[44:45]
	v_max_f32_e32 v34, 0, v34
	v_pk_mul_f32 v[44:45], v[44:45], v[44:45]
	v_max_f32_e32 v35, 0, v35
	v_rcp_f32_e32 v44, v44
	v_rcp_f32_e32 v45, v45
	v_pk_fma_f32 v[48:49], v[38:39], v[38:39], v[68:69]
	v_pk_fma_f32 v[42:43], v[42:43], v[44:45], v[32:33] neg_lo:[1,0,0] neg_hi:[1,0,0]
	v_pk_fma_f32 v[32:33], v[40:41], s[94:95], v[152:153] op_sel_hi:[1,0,0]
	v_pk_fma_f32 v[44:45], v[36:37], v[36:37], v[64:65]
	v_pk_fma_f32 v[32:33], v[40:41], v[32:33], s[96:97] op_sel_hi:[1,1,0]
	v_pk_fma_f32 v[46:47], v[42:43], v[42:43], v[66:67]
	v_pk_fma_f32 v[32:33], v[40:41], v[32:33], s[98:99] op_sel_hi:[1,1,0]
	s_nop 0
	v_pk_fma_f32 v[32:33], v[40:41], v[32:33], s[40:41] op_sel_hi:[1,1,0]
	s_nop 0
	v_pk_fma_f32 v[32:33], v[40:41], v[32:33], s[74:75] op_sel_hi:[1,1,0]
	s_nop 0
	v_pk_fma_f32 v[32:33], v[40:41], v[32:33], s[76:77] op_sel_hi:[1,1,0]
	s_nop 0
	v_pk_mul_f32 v[32:33], v[32:33], v[32:33]
	s_nop 0
	v_pk_mul_f32 v[32:33], v[32:33], v[32:33]
	s_nop 0
	v_pk_mul_f32 v[32:33], v[32:33], v[32:33]
	s_nop 0
	v_pk_mul_f32 v[32:33], v[32:33], v[32:33]
	s_nop 0
	v_rcp_f32_e32 v32, v32
	v_rcp_f32_e32 v33, v33
	s_nop 0
	v_pk_fma_f32 v[40:41], v[40:41], v[32:33], v[34:35] neg_lo:[1,0,0] neg_hi:[1,0,0]
	v_cvt_pk_bf16_f32 v32, v36, v37
	v_cvt_pk_bf16_f32 v33, v38, v39
	v_cvt_pk_bf16_f32 v34, v42, v43
	s_nop 0
	v_cvt_pk_bf16_f32 v35, v40, v41
	global_store_dwordx4 v[52:53], v[32:35], off offset:128 sc1
	v_pk_fma_f32 v[50:51], v[40:41], v[40:41], v[70:71]
	s_nop 0
	v_and_b32_e32 v35, 0x7fffffff, v29
	v_and_b32_e32 v34, 0x7fffffff, v28
	v_pk_fma_f32 v[36:37], v[34:35], s[94:95], v[152:153] op_sel_hi:[1,0,0]
	v_max_f32_e32 v28, v28, v28
	v_pk_fma_f32 v[36:37], v[34:35], v[36:37], s[96:97] op_sel_hi:[1,1,0]
	v_max_f32_e32 v29, v29, v29
	v_pk_fma_f32 v[36:37], v[34:35], v[36:37], s[98:99] op_sel_hi:[1,1,0]
	v_and_b32_e32 v33, 0x7fffffff, v31
	v_pk_fma_f32 v[36:37], v[34:35], v[36:37], s[40:41] op_sel_hi:[1,1,0]
	v_and_b32_e32 v32, 0x7fffffff, v30
	v_pk_fma_f32 v[36:37], v[34:35], v[36:37], s[74:75] op_sel_hi:[1,1,0]
	v_max_f32_e32 v28, 0, v28
	v_pk_fma_f32 v[36:37], v[34:35], v[36:37], s[76:77] op_sel_hi:[1,1,0]
	v_max_f32_e32 v29, 0, v29
	v_pk_mul_f32 v[36:37], v[36:37], v[36:37]
	v_max_f32_e32 v30, v30, v30
	v_pk_mul_f32 v[36:37], v[36:37], v[36:37]
	v_max_f32_e32 v31, v31, v31
	v_pk_mul_f32 v[36:37], v[36:37], v[36:37]
	v_max_f32_e32 v30, 0, v30
	v_pk_mul_f32 v[36:37], v[36:37], v[36:37]
	v_max_f32_e32 v31, 0, v31
	v_rcp_f32_e32 v36, v36
	v_rcp_f32_e32 v37, v37
	s_nop 0
	v_pk_fma_f32 v[34:35], v[34:35], v[36:37], v[28:29] neg_lo:[1,0,0] neg_hi:[1,0,0]
	v_pk_fma_f32 v[28:29], v[32:33], s[94:95], v[152:153] op_sel_hi:[1,0,0]
	s_nop 0
	v_pk_fma_f32 v[28:29], v[32:33], v[28:29], s[96:97] op_sel_hi:[1,1,0]
	s_nop 0
	v_pk_fma_f32 v[28:29], v[32:33], v[28:29], s[98:99] op_sel_hi:[1,1,0]
	s_nop 0
	v_pk_fma_f32 v[28:29], v[32:33], v[28:29], s[40:41] op_sel_hi:[1,1,0]
	s_nop 0
	v_pk_fma_f32 v[28:29], v[32:33], v[28:29], s[74:75] op_sel_hi:[1,1,0]
	s_nop 0
	v_pk_fma_f32 v[28:29], v[32:33], v[28:29], s[76:77] op_sel_hi:[1,1,0]
	s_nop 0
	v_pk_mul_f32 v[28:29], v[28:29], v[28:29]
	s_nop 0
	v_pk_mul_f32 v[28:29], v[28:29], v[28:29]
	s_nop 0
	v_pk_mul_f32 v[28:29], v[28:29], v[28:29]
	s_nop 0
	v_pk_mul_f32 v[28:29], v[28:29], v[28:29]
	s_nop 0
	v_rcp_f32_e32 v28, v28
	v_rcp_f32_e32 v29, v29
	s_nop 0
	v_pk_fma_f32 v[36:37], v[32:33], v[28:29], v[30:31] neg_lo:[1,0,0] neg_hi:[1,0,0]
	v_and_b32_e32 v31, 0x7fffffff, v25
	v_and_b32_e32 v30, 0x7fffffff, v24
	v_pk_fma_f32 v[32:33], v[30:31], s[94:95], v[152:153] op_sel_hi:[1,0,0]
	v_max_f32_e32 v24, v24, v24
	v_pk_fma_f32 v[32:33], v[30:31], v[32:33], s[96:97] op_sel_hi:[1,1,0]
	v_max_f32_e32 v25, v25, v25
	v_pk_fma_f32 v[32:33], v[30:31], v[32:33], s[98:99] op_sel_hi:[1,1,0]
	v_and_b32_e32 v29, 0x7fffffff, v27
	v_pk_fma_f32 v[32:33], v[30:31], v[32:33], s[40:41] op_sel_hi:[1,1,0]
	v_and_b32_e32 v28, 0x7fffffff, v26
	v_pk_fma_f32 v[32:33], v[30:31], v[32:33], s[74:75] op_sel_hi:[1,1,0]
	v_max_f32_e32 v24, 0, v24
	v_pk_fma_f32 v[32:33], v[30:31], v[32:33], s[76:77] op_sel_hi:[1,1,0]
	v_max_f32_e32 v25, 0, v25
	v_pk_mul_f32 v[32:33], v[32:33], v[32:33]
	v_max_f32_e32 v26, v26, v26
	v_pk_mul_f32 v[32:33], v[32:33], v[32:33]
	v_max_f32_e32 v27, v27, v27
	v_pk_mul_f32 v[32:33], v[32:33], v[32:33]
	v_max_f32_e32 v26, 0, v26
	v_pk_mul_f32 v[32:33], v[32:33], v[32:33]
	v_max_f32_e32 v27, 0, v27
	v_rcp_f32_e32 v32, v32
	v_rcp_f32_e32 v33, v33
	s_nop 0
	v_pk_fma_f32 v[38:39], v[30:31], v[32:33], v[24:25] neg_lo:[1,0,0] neg_hi:[1,0,0]
	v_pk_fma_f32 v[24:25], v[28:29], s[94:95], v[152:153] op_sel_hi:[1,0,0]
	v_cvt_pk_bf16_f32 v32, v34, v35
	v_cvt_pk_bf16_f32 v33, v36, v37
	s_nop 0
	v_pk_fma_f32 v[24:25], v[28:29], v[24:25], s[96:97] op_sel_hi:[1,1,0]
	s_nop 0
	v_pk_fma_f32 v[24:25], v[28:29], v[24:25], s[98:99] op_sel_hi:[1,1,0]
	s_nop 0
	v_pk_fma_f32 v[24:25], v[28:29], v[24:25], s[40:41] op_sel_hi:[1,1,0]
	s_nop 0
	v_pk_fma_f32 v[24:25], v[28:29], v[24:25], s[74:75] op_sel_hi:[1,1,0]
	s_nop 0
	v_pk_fma_f32 v[24:25], v[28:29], v[24:25], s[76:77] op_sel_hi:[1,1,0]
	s_nop 0
	v_pk_mul_f32 v[24:25], v[24:25], v[24:25]
	s_nop 0
	v_pk_mul_f32 v[24:25], v[24:25], v[24:25]
	s_nop 0
	v_pk_mul_f32 v[24:25], v[24:25], v[24:25]
	s_nop 0
	v_pk_mul_f32 v[24:25], v[24:25], v[24:25]
	s_nop 0
	v_rcp_f32_e32 v24, v24
	v_rcp_f32_e32 v25, v25
	s_nop 0
	v_pk_fma_f32 v[40:41], v[28:29], v[24:25], v[26:27] neg_lo:[1,0,0] neg_hi:[1,0,0]
	v_pk_fma_f32 v[28:29], v[36:37], v[36:37], v[58:59]
	v_mov_b32_e32 v37, s5
	v_or_b32_e32 v36, s4, v138
	v_lshlrev_b64 v[36:37], 10, v[36:37]
	v_pk_fma_f32 v[24:25], v[34:35], v[34:35], v[54:55]
	v_cvt_pk_bf16_f32 v34, v38, v39
	v_cvt_pk_bf16_f32 v35, v40, v41
	v_lshl_add_u64 v[36:37], v[142:143], 0, v[36:37]
	global_store_dwordx4 v[36:37], v[32:35], off sc1
	v_pk_fma_f32 v[26:27], v[38:39], v[38:39], v[56:57]
	v_pk_fma_f32 v[30:31], v[40:41], v[40:41], v[60:61]
	v_and_b32_e32 v35, 0x7fffffff, v21
	v_and_b32_e32 v34, 0x7fffffff, v20
	v_pk_fma_f32 v[38:39], v[34:35], s[94:95], v[152:153] op_sel_hi:[1,0,0]
	v_max_f32_e32 v20, v20, v20
	v_pk_fma_f32 v[38:39], v[34:35], v[38:39], s[96:97] op_sel_hi:[1,1,0]
	v_max_f32_e32 v21, v21, v21
	v_pk_fma_f32 v[38:39], v[34:35], v[38:39], s[98:99] op_sel_hi:[1,1,0]
	v_and_b32_e32 v33, 0x7fffffff, v23
	v_pk_fma_f32 v[38:39], v[34:35], v[38:39], s[40:41] op_sel_hi:[1,1,0]
	v_and_b32_e32 v32, 0x7fffffff, v22
	v_pk_fma_f32 v[38:39], v[34:35], v[38:39], s[74:75] op_sel_hi:[1,1,0]
	v_max_f32_e32 v20, 0, v20
	v_pk_fma_f32 v[38:39], v[34:35], v[38:39], s[76:77] op_sel_hi:[1,1,0]
	v_max_f32_e32 v21, 0, v21
	v_pk_mul_f32 v[38:39], v[38:39], v[38:39]
	v_max_f32_e32 v22, v22, v22
	v_pk_mul_f32 v[38:39], v[38:39], v[38:39]
	v_max_f32_e32 v23, v23, v23
	v_pk_mul_f32 v[38:39], v[38:39], v[38:39]
	v_max_f32_e32 v22, 0, v22
	v_pk_mul_f32 v[38:39], v[38:39], v[38:39]
	v_max_f32_e32 v23, 0, v23
	v_rcp_f32_e32 v38, v38
	v_rcp_f32_e32 v39, v39
	s_nop 0
	v_pk_fma_f32 v[20:21], v[34:35], v[38:39], v[20:21] neg_lo:[1,0,0] neg_hi:[1,0,0]
	v_pk_fma_f32 v[34:35], v[32:33], s[94:95], v[152:153] op_sel_hi:[1,0,0]
	s_nop 0
	v_pk_fma_f32 v[34:35], v[32:33], v[34:35], s[96:97] op_sel_hi:[1,1,0]
	s_nop 0
	v_pk_fma_f32 v[34:35], v[32:33], v[34:35], s[98:99] op_sel_hi:[1,1,0]
	s_nop 0
	v_pk_fma_f32 v[34:35], v[32:33], v[34:35], s[40:41] op_sel_hi:[1,1,0]
	s_nop 0
	v_pk_fma_f32 v[34:35], v[32:33], v[34:35], s[74:75] op_sel_hi:[1,1,0]
	s_nop 0
	v_pk_fma_f32 v[34:35], v[32:33], v[34:35], s[76:77] op_sel_hi:[1,1,0]
	s_nop 0
	v_pk_mul_f32 v[34:35], v[34:35], v[34:35]
	s_nop 0
	v_pk_mul_f32 v[34:35], v[34:35], v[34:35]
	s_nop 0
	v_pk_mul_f32 v[34:35], v[34:35], v[34:35]
	s_nop 0
	v_pk_mul_f32 v[34:35], v[34:35], v[34:35]
	s_nop 0
	v_rcp_f32_e32 v34, v34
	v_rcp_f32_e32 v35, v35
	s_nop 0
	v_pk_fma_f32 v[22:23], v[32:33], v[34:35], v[22:23] neg_lo:[1,0,0] neg_hi:[1,0,0]
	v_and_b32_e32 v35, 0x7fffffff, v17
	v_and_b32_e32 v34, 0x7fffffff, v16
	v_pk_fma_f32 v[38:39], v[34:35], s[94:95], v[152:153] op_sel_hi:[1,0,0]
	v_max_f32_e32 v16, v16, v16
	v_pk_fma_f32 v[38:39], v[34:35], v[38:39], s[96:97] op_sel_hi:[1,1,0]
	v_max_f32_e32 v17, v17, v17
	v_pk_fma_f32 v[38:39], v[34:35], v[38:39], s[98:99] op_sel_hi:[1,1,0]
	v_and_b32_e32 v33, 0x7fffffff, v19
	v_pk_fma_f32 v[38:39], v[34:35], v[38:39], s[40:41] op_sel_hi:[1,1,0]
	v_and_b32_e32 v32, 0x7fffffff, v18
	v_pk_fma_f32 v[38:39], v[34:35], v[38:39], s[74:75] op_sel_hi:[1,1,0]
	v_max_f32_e32 v16, 0, v16
	v_pk_fma_f32 v[38:39], v[34:35], v[38:39], s[76:77] op_sel_hi:[1,1,0]
	v_max_f32_e32 v17, 0, v17
	v_pk_mul_f32 v[38:39], v[38:39], v[38:39]
	v_max_f32_e32 v18, v18, v18
	v_pk_mul_f32 v[38:39], v[38:39], v[38:39]
	v_max_f32_e32 v19, v19, v19
	v_pk_mul_f32 v[38:39], v[38:39], v[38:39]
	v_max_f32_e32 v18, 0, v18
	v_pk_mul_f32 v[38:39], v[38:39], v[38:39]
	v_max_f32_e32 v19, 0, v19
	v_rcp_f32_e32 v38, v38
	v_rcp_f32_e32 v39, v39
	v_pk_fma_f32 v[42:43], v[22:23], v[22:23], v[48:49]
	v_pk_fma_f32 v[34:35], v[34:35], v[38:39], v[16:17] neg_lo:[1,0,0] neg_hi:[1,0,0]
	v_pk_fma_f32 v[16:17], v[32:33], s[94:95], v[152:153] op_sel_hi:[1,0,0]
	v_pk_fma_f32 v[38:39], v[20:21], v[20:21], v[44:45]
	v_pk_fma_f32 v[16:17], v[32:33], v[16:17], s[96:97] op_sel_hi:[1,1,0]
	v_pk_fma_f32 v[40:41], v[34:35], v[34:35], v[46:47]
	v_pk_fma_f32 v[16:17], v[32:33], v[16:17], s[98:99] op_sel_hi:[1,1,0]
	s_nop 0
	v_pk_fma_f32 v[16:17], v[32:33], v[16:17], s[40:41] op_sel_hi:[1,1,0]
	s_nop 0
	v_pk_fma_f32 v[16:17], v[32:33], v[16:17], s[74:75] op_sel_hi:[1,1,0]
	s_nop 0
	v_pk_fma_f32 v[16:17], v[32:33], v[16:17], s[76:77] op_sel_hi:[1,1,0]
	s_nop 0
	v_pk_mul_f32 v[16:17], v[16:17], v[16:17]
	s_nop 0
	v_pk_mul_f32 v[16:17], v[16:17], v[16:17]
	s_nop 0
	v_pk_mul_f32 v[16:17], v[16:17], v[16:17]
	s_nop 0
	v_pk_mul_f32 v[16:17], v[16:17], v[16:17]
	s_nop 0
	v_rcp_f32_e32 v16, v16
	v_rcp_f32_e32 v17, v17
	s_nop 0
	v_pk_fma_f32 v[32:33], v[32:33], v[16:17], v[18:19] neg_lo:[1,0,0] neg_hi:[1,0,0]
	v_cvt_pk_bf16_f32 v16, v20, v21
	v_mov_b32_e32 v21, s1
	v_or_b32_e32 v20, s0, v138
	v_lshlrev_b64 v[20:21], 10, v[20:21]
	v_cvt_pk_bf16_f32 v17, v22, v23
	v_cvt_pk_bf16_f32 v18, v34, v35
	v_cvt_pk_bf16_f32 v19, v32, v33
	v_lshl_add_u64 v[20:21], v[142:143], 0, v[20:21]
	global_store_dwordx4 v[20:21], v[16:19], off sc1
	v_readlane_b32 s0, v254, 18
	v_readlane_b32 s1, v254, 19
	v_and_b32_e32 v19, 0x7fffffff, v13
	v_and_b32_e32 v18, 0x7fffffff, v12
	v_pk_fma_f32 v[22:23], v[18:19], s[94:95], v[152:153] op_sel_hi:[1,0,0]
	v_max_f32_e32 v12, v12, v12
	v_pk_fma_f32 v[22:23], v[18:19], v[22:23], s[96:97] op_sel_hi:[1,1,0]
	v_max_f32_e32 v13, v13, v13
	v_pk_fma_f32 v[22:23], v[18:19], v[22:23], s[98:99] op_sel_hi:[1,1,0]
	v_and_b32_e32 v17, 0x7fffffff, v15
	v_pk_fma_f32 v[22:23], v[18:19], v[22:23], s[40:41] op_sel_hi:[1,1,0]
	v_and_b32_e32 v16, 0x7fffffff, v14
	v_pk_fma_f32 v[22:23], v[18:19], v[22:23], s[74:75] op_sel_hi:[1,1,0]
	v_max_f32_e32 v12, 0, v12
	v_pk_fma_f32 v[22:23], v[18:19], v[22:23], s[76:77] op_sel_hi:[1,1,0]
	v_max_f32_e32 v13, 0, v13
	v_pk_mul_f32 v[22:23], v[22:23], v[22:23]
	v_max_f32_e32 v14, v14, v14
	v_pk_mul_f32 v[22:23], v[22:23], v[22:23]
	v_max_f32_e32 v15, v15, v15
	v_pk_mul_f32 v[22:23], v[22:23], v[22:23]
	v_max_f32_e32 v14, 0, v14
	v_pk_mul_f32 v[22:23], v[22:23], v[22:23]
	v_max_f32_e32 v15, 0, v15
	v_rcp_f32_e32 v22, v22
	v_rcp_f32_e32 v23, v23
	v_pk_fma_f32 v[44:45], v[32:33], v[32:33], v[50:51]
	v_pk_fma_f32 v[12:13], v[18:19], v[22:23], v[12:13] neg_lo:[1,0,0] neg_hi:[1,0,0]
	v_pk_fma_f32 v[18:19], v[16:17], s[94:95], v[152:153] op_sel_hi:[1,0,0]
	s_nop 0
	v_pk_fma_f32 v[18:19], v[16:17], v[18:19], s[96:97] op_sel_hi:[1,1,0]
	s_nop 0
	v_pk_fma_f32 v[18:19], v[16:17], v[18:19], s[98:99] op_sel_hi:[1,1,0]
	s_nop 0
	v_pk_fma_f32 v[18:19], v[16:17], v[18:19], s[40:41] op_sel_hi:[1,1,0]
	s_nop 0
	v_pk_fma_f32 v[18:19], v[16:17], v[18:19], s[74:75] op_sel_hi:[1,1,0]
	s_nop 0
	v_pk_fma_f32 v[18:19], v[16:17], v[18:19], s[76:77] op_sel_hi:[1,1,0]
	s_nop 0
	v_pk_mul_f32 v[18:19], v[18:19], v[18:19]
	s_nop 0
	v_pk_mul_f32 v[18:19], v[18:19], v[18:19]
	s_nop 0
	v_pk_mul_f32 v[18:19], v[18:19], v[18:19]
	s_nop 0
	v_pk_mul_f32 v[18:19], v[18:19], v[18:19]
	s_nop 0
	v_rcp_f32_e32 v18, v18
	v_rcp_f32_e32 v19, v19
	s_nop 0
	v_pk_fma_f32 v[14:15], v[16:17], v[18:19], v[14:15] neg_lo:[1,0,0] neg_hi:[1,0,0]
	v_and_b32_e32 v19, 0x7fffffff, v9
	v_and_b32_e32 v18, 0x7fffffff, v8
	v_pk_fma_f32 v[22:23], v[18:19], s[94:95], v[152:153] op_sel_hi:[1,0,0]
	v_max_f32_e32 v8, v8, v8
	v_pk_fma_f32 v[22:23], v[18:19], v[22:23], s[96:97] op_sel_hi:[1,1,0]
	v_max_f32_e32 v9, v9, v9
	v_pk_fma_f32 v[22:23], v[18:19], v[22:23], s[98:99] op_sel_hi:[1,1,0]
	v_and_b32_e32 v17, 0x7fffffff, v11
	v_pk_fma_f32 v[22:23], v[18:19], v[22:23], s[40:41] op_sel_hi:[1,1,0]
	v_and_b32_e32 v16, 0x7fffffff, v10
	v_pk_fma_f32 v[22:23], v[18:19], v[22:23], s[74:75] op_sel_hi:[1,1,0]
	v_max_f32_e32 v8, 0, v8
	v_pk_fma_f32 v[22:23], v[18:19], v[22:23], s[76:77] op_sel_hi:[1,1,0]
	v_max_f32_e32 v9, 0, v9
	v_pk_mul_f32 v[22:23], v[22:23], v[22:23]
	v_max_f32_e32 v10, v10, v10
	v_pk_mul_f32 v[22:23], v[22:23], v[22:23]
	v_max_f32_e32 v11, v11, v11
	v_pk_mul_f32 v[22:23], v[22:23], v[22:23]
	v_max_f32_e32 v10, 0, v10
	v_pk_mul_f32 v[22:23], v[22:23], v[22:23]
	v_max_f32_e32 v11, 0, v11
	v_rcp_f32_e32 v22, v22
	v_rcp_f32_e32 v23, v23
	s_nop 0
	v_pk_fma_f32 v[18:19], v[18:19], v[22:23], v[8:9] neg_lo:[1,0,0] neg_hi:[1,0,0]
	v_pk_fma_f32 v[8:9], v[16:17], s[94:95], v[152:153] op_sel_hi:[1,0,0]
	v_pk_fma_f32 v[22:23], v[12:13], v[12:13], v[24:25]
	v_pk_fma_f32 v[8:9], v[16:17], v[8:9], s[96:97] op_sel_hi:[1,1,0]
	v_pk_fma_f32 v[24:25], v[18:19], v[18:19], v[26:27]
	v_pk_fma_f32 v[8:9], v[16:17], v[8:9], s[98:99] op_sel_hi:[1,1,0]
	v_pk_fma_f32 v[26:27], v[14:15], v[14:15], v[28:29]
	v_pk_fma_f32 v[8:9], v[16:17], v[8:9], s[40:41] op_sel_hi:[1,1,0]
	s_nop 0
	v_pk_fma_f32 v[8:9], v[16:17], v[8:9], s[74:75] op_sel_hi:[1,1,0]
	s_nop 0
	v_pk_fma_f32 v[8:9], v[16:17], v[8:9], s[76:77] op_sel_hi:[1,1,0]
	s_nop 0
	v_pk_mul_f32 v[8:9], v[8:9], v[8:9]
	s_nop 0
	v_pk_mul_f32 v[8:9], v[8:9], v[8:9]
	s_nop 0
	v_pk_mul_f32 v[8:9], v[8:9], v[8:9]
	s_nop 0
	v_pk_mul_f32 v[8:9], v[8:9], v[8:9]
	s_nop 0
	v_rcp_f32_e32 v8, v8
	v_rcp_f32_e32 v9, v9
	s_nop 0
	v_pk_fma_f32 v[16:17], v[16:17], v[8:9], v[10:11] neg_lo:[1,0,0] neg_hi:[1,0,0]
	v_cvt_pk_bf16_f32 v8, v12, v13
	v_cvt_pk_bf16_f32 v9, v14, v15
	v_cvt_pk_bf16_f32 v10, v18, v19
	s_nop 0
	v_cvt_pk_bf16_f32 v11, v16, v17
	global_store_dwordx4 v[36:37], v[8:11], off offset:128 sc1
	v_pk_fma_f32 v[28:29], v[16:17], v[16:17], v[30:31]
	s_nop 0
	v_and_b32_e32 v11, 0x7fffffff, v5
	v_and_b32_e32 v10, 0x7fffffff, v4
	v_pk_fma_f32 v[12:13], v[10:11], s[94:95], v[152:153] op_sel_hi:[1,0,0]
	v_max_f32_e32 v4, v4, v4
	v_pk_fma_f32 v[12:13], v[10:11], v[12:13], s[96:97] op_sel_hi:[1,1,0]
	v_max_f32_e32 v5, v5, v5
	v_pk_fma_f32 v[12:13], v[10:11], v[12:13], s[98:99] op_sel_hi:[1,1,0]
	v_and_b32_e32 v9, 0x7fffffff, v7
	v_pk_fma_f32 v[12:13], v[10:11], v[12:13], s[40:41] op_sel_hi:[1,1,0]
	v_and_b32_e32 v8, 0x7fffffff, v6
	v_pk_fma_f32 v[12:13], v[10:11], v[12:13], s[74:75] op_sel_hi:[1,1,0]
	v_max_f32_e32 v4, 0, v4
	v_pk_fma_f32 v[12:13], v[10:11], v[12:13], s[76:77] op_sel_hi:[1,1,0]
	v_max_f32_e32 v5, 0, v5
	v_pk_mul_f32 v[12:13], v[12:13], v[12:13]
	v_max_f32_e32 v6, v6, v6
	v_pk_mul_f32 v[12:13], v[12:13], v[12:13]
	v_max_f32_e32 v7, v7, v7
	v_pk_mul_f32 v[12:13], v[12:13], v[12:13]
	v_max_f32_e32 v6, 0, v6
	v_pk_mul_f32 v[12:13], v[12:13], v[12:13]
	v_max_f32_e32 v7, 0, v7
	v_rcp_f32_e32 v12, v12
	v_rcp_f32_e32 v13, v13
	s_nop 0
	v_pk_fma_f32 v[4:5], v[10:11], v[12:13], v[4:5] neg_lo:[1,0,0] neg_hi:[1,0,0]
	v_pk_fma_f32 v[10:11], v[8:9], s[94:95], v[152:153] op_sel_hi:[1,0,0]
	s_nop 0
	v_pk_fma_f32 v[10:11], v[8:9], v[10:11], s[96:97] op_sel_hi:[1,1,0]
	s_nop 0
	v_pk_fma_f32 v[10:11], v[8:9], v[10:11], s[98:99] op_sel_hi:[1,1,0]
	s_nop 0
	v_pk_fma_f32 v[10:11], v[8:9], v[10:11], s[40:41] op_sel_hi:[1,1,0]
	s_nop 0
	v_pk_fma_f32 v[10:11], v[8:9], v[10:11], s[74:75] op_sel_hi:[1,1,0]
	s_nop 0
	v_pk_fma_f32 v[10:11], v[8:9], v[10:11], s[76:77] op_sel_hi:[1,1,0]
	s_nop 0
	v_pk_mul_f32 v[10:11], v[10:11], v[10:11]
	s_nop 0
	v_pk_mul_f32 v[10:11], v[10:11], v[10:11]
	s_nop 0
	v_pk_mul_f32 v[10:11], v[10:11], v[10:11]
	s_nop 0
	v_pk_mul_f32 v[10:11], v[10:11], v[10:11]
	s_nop 0
	v_rcp_f32_e32 v10, v10
	v_rcp_f32_e32 v11, v11
	s_nop 0
	v_pk_fma_f32 v[6:7], v[8:9], v[10:11], v[6:7] neg_lo:[1,0,0] neg_hi:[1,0,0]
	v_and_b32_e32 v11, 0x7fffffff, v1
	v_and_b32_e32 v10, 0x7fffffff, v0
	v_pk_fma_f32 v[12:13], v[10:11], s[94:95], v[152:153] op_sel_hi:[1,0,0]
	v_max_f32_e32 v0, v0, v0
	v_pk_fma_f32 v[12:13], v[10:11], v[12:13], s[96:97] op_sel_hi:[1,1,0]
	v_max_f32_e32 v1, v1, v1
	v_pk_fma_f32 v[12:13], v[10:11], v[12:13], s[98:99] op_sel_hi:[1,1,0]
	v_and_b32_e32 v9, 0x7fffffff, v3
	v_pk_fma_f32 v[12:13], v[10:11], v[12:13], s[40:41] op_sel_hi:[1,1,0]
	v_and_b32_e32 v8, 0x7fffffff, v2
	v_pk_fma_f32 v[12:13], v[10:11], v[12:13], s[74:75] op_sel_hi:[1,1,0]
	v_max_f32_e32 v0, 0, v0
	v_pk_fma_f32 v[12:13], v[10:11], v[12:13], s[76:77] op_sel_hi:[1,1,0]
	v_max_f32_e32 v1, 0, v1
	v_pk_mul_f32 v[12:13], v[12:13], v[12:13]
	v_max_f32_e32 v2, v2, v2
	v_pk_mul_f32 v[12:13], v[12:13], v[12:13]
	v_max_f32_e32 v3, v3, v3
	v_pk_mul_f32 v[12:13], v[12:13], v[12:13]
	v_max_f32_e32 v2, 0, v2
	v_pk_mul_f32 v[12:13], v[12:13], v[12:13]
	v_max_f32_e32 v3, 0, v3
	v_rcp_f32_e32 v12, v12
	v_rcp_f32_e32 v13, v13
	v_pk_fma_f32 v[16:17], v[6:7], v[6:7], v[42:43]
	v_pk_fma_f32 v[10:11], v[10:11], v[12:13], v[0:1] neg_lo:[1,0,0] neg_hi:[1,0,0]
	v_pk_fma_f32 v[0:1], v[8:9], s[94:95], v[152:153] op_sel_hi:[1,0,0]
	v_pk_fma_f32 v[12:13], v[4:5], v[4:5], v[38:39]
	v_pk_fma_f32 v[0:1], v[8:9], v[0:1], s[96:97] op_sel_hi:[1,1,0]
	v_pk_fma_f32 v[14:15], v[10:11], v[10:11], v[40:41]
	v_pk_fma_f32 v[0:1], v[8:9], v[0:1], s[98:99] op_sel_hi:[1,1,0]
	s_nop 0
	v_pk_fma_f32 v[0:1], v[8:9], v[0:1], s[40:41] op_sel_hi:[1,1,0]
	s_nop 0
	v_pk_fma_f32 v[0:1], v[8:9], v[0:1], s[74:75] op_sel_hi:[1,1,0]
	s_nop 0
	v_pk_fma_f32 v[0:1], v[8:9], v[0:1], s[76:77] op_sel_hi:[1,1,0]
	s_nop 0
	v_pk_mul_f32 v[0:1], v[0:1], v[0:1]
	s_nop 0
	v_pk_mul_f32 v[0:1], v[0:1], v[0:1]
	s_nop 0
	v_pk_mul_f32 v[0:1], v[0:1], v[0:1]
	s_nop 0
	v_pk_mul_f32 v[0:1], v[0:1], v[0:1]
	s_nop 0
	v_rcp_f32_e32 v0, v0
	v_rcp_f32_e32 v1, v1
	s_nop 0
	v_pk_fma_f32 v[8:9], v[8:9], v[0:1], v[2:3] neg_lo:[1,0,0] neg_hi:[1,0,0]
	v_cvt_pk_bf16_f32 v0, v4, v5
	v_cvt_pk_bf16_f32 v1, v6, v7
	v_cvt_pk_bf16_f32 v2, v10, v11
	s_nop 0
	v_cvt_pk_bf16_f32 v3, v8, v9
	global_store_dwordx4 v[20:21], v[0:3], off offset:128 sc1
	v_pk_fma_f32 v[18:19], v[8:9], v[8:9], v[44:45]
	s_nop 0
	v_add_f32_dpp v0, v22, v22 row_ror:8 row_mask:0xf bank_mask:0xf bound_ctrl:1
	v_add_f32_dpp v1, v23, v23 row_ror:8 row_mask:0xf bank_mask:0xf bound_ctrl:1
	s_nop 0
	v_add_f32_dpp v0, v0, v0 row_ror:4 row_mask:0xf bank_mask:0xf bound_ctrl:1
	v_add_f32_dpp v1, v1, v1 row_ror:4 row_mask:0xf bank_mask:0xf bound_ctrl:1
	s_nop 0
	v_add_f32_dpp v0, v0, v0 row_ror:2 row_mask:0xf bank_mask:0xf bound_ctrl:1
	v_add_f32_dpp v1, v1, v1 row_ror:2 row_mask:0xf bank_mask:0xf bound_ctrl:1
	s_nop 0
	v_add_f32_dpp v0, v0, v0 row_ror:1 row_mask:0xf bank_mask:0xf bound_ctrl:1
	v_cndmask_b32_e64 v0, 0, v0, s[0:1]
	v_readlane_b32 s0, v254, 20
	v_add_f32_dpp v1, v1, v1 row_ror:1 row_mask:0xf bank_mask:0xf bound_ctrl:1
	v_readlane_b32 s1, v254, 21
	s_nop 1
	v_cndmask_b32_e64 v0, v0, v1, s[0:1]
	v_add_f32_dpp v1, v26, v26 row_ror:8 row_mask:0xf bank_mask:0xf bound_ctrl:1
	v_readlane_b32 s0, v254, 22
	v_readlane_b32 s1, v254, 23
	v_add_f32_dpp v1, v1, v1 row_ror:4 row_mask:0xf bank_mask:0xf bound_ctrl:1
	s_nop 1
	v_add_f32_dpp v1, v1, v1 row_ror:2 row_mask:0xf bank_mask:0xf bound_ctrl:1
	s_nop 1
	v_add_f32_dpp v1, v1, v1 row_ror:1 row_mask:0xf bank_mask:0xf bound_ctrl:1
	v_cndmask_b32_e64 v0, v0, v1, s[0:1]
	v_readlane_b32 s0, v254, 24
	v_add_f32_dpp v1, v27, v27 row_ror:8 row_mask:0xf bank_mask:0xf bound_ctrl:1
	v_readlane_b32 s1, v254, 25
	s_nop 0
	v_add_f32_dpp v1, v1, v1 row_ror:4 row_mask:0xf bank_mask:0xf bound_ctrl:1
	s_nop 1
	v_add_f32_dpp v1, v1, v1 row_ror:2 row_mask:0xf bank_mask:0xf bound_ctrl:1
	s_nop 1
	v_add_f32_dpp v1, v1, v1 row_ror:1 row_mask:0xf bank_mask:0xf bound_ctrl:1
	v_cndmask_b32_e64 v0, v0, v1, s[0:1]
	v_readlane_b32 s0, v254, 26
	v_add_f32_dpp v1, v24, v24 row_ror:8 row_mask:0xf bank_mask:0xf bound_ctrl:1
	v_readlane_b32 s1, v254, 27
	s_nop 0
	v_add_f32_dpp v1, v1, v1 row_ror:4 row_mask:0xf bank_mask:0xf bound_ctrl:1
	s_nop 1
	v_add_f32_dpp v1, v1, v1 row_ror:2 row_mask:0xf bank_mask:0xf bound_ctrl:1
	s_nop 1
	v_add_f32_dpp v1, v1, v1 row_ror:1 row_mask:0xf bank_mask:0xf bound_ctrl:1
	v_cndmask_b32_e64 v0, v0, v1, s[0:1]
	v_readlane_b32 s0, v254, 28
	v_add_f32_dpp v1, v25, v25 row_ror:8 row_mask:0xf bank_mask:0xf bound_ctrl:1
	v_readlane_b32 s1, v254, 29
	s_nop 0
	v_add_f32_dpp v1, v1, v1 row_ror:4 row_mask:0xf bank_mask:0xf bound_ctrl:1
	s_nop 1
	v_add_f32_dpp v1, v1, v1 row_ror:2 row_mask:0xf bank_mask:0xf bound_ctrl:1
	s_nop 1
	v_add_f32_dpp v1, v1, v1 row_ror:1 row_mask:0xf bank_mask:0xf bound_ctrl:1
	v_cndmask_b32_e64 v0, v0, v1, s[0:1]
	v_readlane_b32 s0, v254, 30
	v_add_f32_dpp v1, v28, v28 row_ror:8 row_mask:0xf bank_mask:0xf bound_ctrl:1
	v_readlane_b32 s1, v254, 31
	s_nop 0
	v_add_f32_dpp v1, v1, v1 row_ror:4 row_mask:0xf bank_mask:0xf bound_ctrl:1
	s_nop 1
	v_add_f32_dpp v1, v1, v1 row_ror:2 row_mask:0xf bank_mask:0xf bound_ctrl:1
	s_nop 1
	v_add_f32_dpp v1, v1, v1 row_ror:1 row_mask:0xf bank_mask:0xf bound_ctrl:1
	v_cndmask_b32_e64 v0, v0, v1, s[0:1]
	s_nop 0
	v_add_f32_dpp v1, v29, v29 row_ror:8 row_mask:0xf bank_mask:0xf bound_ctrl:1
	s_nop 1
	v_add_f32_dpp v1, v1, v1 row_ror:4 row_mask:0xf bank_mask:0xf bound_ctrl:1
	s_nop 1
	v_add_f32_dpp v1, v1, v1 row_ror:2 row_mask:0xf bank_mask:0xf bound_ctrl:1
	s_nop 1
	v_add_f32_dpp v1, v1, v1 row_ror:1 row_mask:0xf bank_mask:0xf bound_ctrl:1
	v_cndmask_b32_e64 v0, v0, v1, s[16:17]
	s_nop 0
	v_add_f32_dpp v1, v12, v12 row_ror:8 row_mask:0xf bank_mask:0xf bound_ctrl:1
	s_nop 1
	v_add_f32_dpp v1, v1, v1 row_ror:4 row_mask:0xf bank_mask:0xf bound_ctrl:1
	s_nop 1
	v_add_f32_dpp v1, v1, v1 row_ror:2 row_mask:0xf bank_mask:0xf bound_ctrl:1
	s_nop 1
	v_add_f32_dpp v1, v1, v1 row_ror:1 row_mask:0xf bank_mask:0xf bound_ctrl:1
	v_cndmask_b32_e64 v0, v0, v1, s[18:19]
	s_nop 0
	v_add_f32_dpp v1, v13, v13 row_ror:8 row_mask:0xf bank_mask:0xf bound_ctrl:1
	s_nop 1
	v_add_f32_dpp v1, v1, v1 row_ror:4 row_mask:0xf bank_mask:0xf bound_ctrl:1
	s_nop 1
	v_add_f32_dpp v1, v1, v1 row_ror:2 row_mask:0xf bank_mask:0xf bound_ctrl:1
	s_nop 1
	v_add_f32_dpp v1, v1, v1 row_ror:1 row_mask:0xf bank_mask:0xf bound_ctrl:1
	v_cndmask_b32_e64 v0, v0, v1, s[20:21]
	s_nop 0
	v_add_f32_dpp v1, v16, v16 row_ror:8 row_mask:0xf bank_mask:0xf bound_ctrl:1
	s_nop 1
	v_add_f32_dpp v1, v1, v1 row_ror:4 row_mask:0xf bank_mask:0xf bound_ctrl:1
	s_nop 1
	v_add_f32_dpp v1, v1, v1 row_ror:2 row_mask:0xf bank_mask:0xf bound_ctrl:1
	s_nop 1
	v_add_f32_dpp v1, v1, v1 row_ror:1 row_mask:0xf bank_mask:0xf bound_ctrl:1
	v_cndmask_b32_e64 v0, v0, v1, s[22:23]
	s_nop 0
	v_add_f32_dpp v1, v17, v17 row_ror:8 row_mask:0xf bank_mask:0xf bound_ctrl:1
	s_nop 1
	v_add_f32_dpp v1, v1, v1 row_ror:4 row_mask:0xf bank_mask:0xf bound_ctrl:1
	s_nop 1
	v_add_f32_dpp v1, v1, v1 row_ror:2 row_mask:0xf bank_mask:0xf bound_ctrl:1
	s_nop 1
	v_add_f32_dpp v1, v1, v1 row_ror:1 row_mask:0xf bank_mask:0xf bound_ctrl:1
	v_cndmask_b32_e64 v0, v0, v1, s[24:25]
	s_nop 0
	v_add_f32_dpp v1, v14, v14 row_ror:8 row_mask:0xf bank_mask:0xf bound_ctrl:1
	s_nop 1
	v_add_f32_dpp v1, v1, v1 row_ror:4 row_mask:0xf bank_mask:0xf bound_ctrl:1
	s_nop 1
	v_add_f32_dpp v1, v1, v1 row_ror:2 row_mask:0xf bank_mask:0xf bound_ctrl:1
	s_nop 1
	v_add_f32_dpp v1, v1, v1 row_ror:1 row_mask:0xf bank_mask:0xf bound_ctrl:1
	v_cndmask_b32_e64 v0, v0, v1, s[26:27]
	s_nop 0
	v_add_f32_dpp v1, v15, v15 row_ror:8 row_mask:0xf bank_mask:0xf bound_ctrl:1
	s_nop 1
	v_add_f32_dpp v1, v1, v1 row_ror:4 row_mask:0xf bank_mask:0xf bound_ctrl:1
	s_nop 1
	v_add_f32_dpp v1, v1, v1 row_ror:2 row_mask:0xf bank_mask:0xf bound_ctrl:1
	s_nop 1
	v_add_f32_dpp v1, v1, v1 row_ror:1 row_mask:0xf bank_mask:0xf bound_ctrl:1
	v_cndmask_b32_e64 v0, v0, v1, s[28:29]
	s_nop 0
	v_add_f32_dpp v1, v18, v18 row_ror:8 row_mask:0xf bank_mask:0xf bound_ctrl:1
	s_nop 1
	v_add_f32_dpp v1, v1, v1 row_ror:4 row_mask:0xf bank_mask:0xf bound_ctrl:1
	s_nop 1
	v_add_f32_dpp v1, v1, v1 row_ror:2 row_mask:0xf bank_mask:0xf bound_ctrl:1
	s_nop 1
	v_add_f32_dpp v1, v1, v1 row_ror:1 row_mask:0xf bank_mask:0xf bound_ctrl:1
	v_cndmask_b32_e64 v0, v0, v1, s[30:31]
	s_nop 0
	v_add_f32_dpp v1, v19, v19 row_ror:8 row_mask:0xf bank_mask:0xf bound_ctrl:1
	s_nop 1
	v_add_f32_dpp v1, v1, v1 row_ror:4 row_mask:0xf bank_mask:0xf bound_ctrl:1
	s_nop 1
	v_add_f32_dpp v1, v1, v1 row_ror:2 row_mask:0xf bank_mask:0xf bound_ctrl:1
	s_nop 1
	v_add_f32_dpp v1, v1, v1 row_ror:1 row_mask:0xf bank_mask:0xf bound_ctrl:1
	v_cndmask_b32_e64 v0, v0, v1, s[34:35]
	s_cbranch_vccnz .LBB0_188
	ds_write_b32 v158, v0
